# diff-attention component-1 epilogue: AO rows staged through a per-wave 4 KiB LDS slice (V buffer 1) and stored as 16-byte write-through (sc1) stores, 16 per lane instead of 64 dword stores; rest as eb
# speedup vs baseline: 1.0104x; 1.0104x over previous
.LBB0_445:
	s_and_saveexec_b64 s[56:57], s[4:5]
	ds_write_b32 v247, v250
	s_or_b64 exec, exec, s[56:57]
	s_waitcnt lgkmcnt(0)
	s_movk_i32 s83, 0x800
	v_lshl_add_u32 v0, v211, 2, s21
	ds_read2_b32 v[2:3], v0 offset1:1
	s_add_u32 s0, s78, s6
	s_addc_u32 s4, s79, s7
	s_waitcnt lgkmcnt(0)
	v_rcp_f32_e32 v4, v2
	v_rcp_f32_e32 v150, v3
	ds_read2_b32 v[2:3], v0 offset0:2 offset1:3
	v_mul_f32_e32 v130, v130, v4
	v_mul_f32_e32 v114, v114, v4
	v_mul_f32_e32 v98, v98, v4
	s_waitcnt lgkmcnt(0)
	v_rcp_f32_e32 v149, v2
	v_rcp_f32_e32 v148, v3
	ds_read2_b32 v[2:3], v0 offset0:8 offset1:9
	v_mul_f32_e32 v82, v82, v4
	v_mul_f32_e32 v66, v66, v4
	v_mul_f32_e32 v50, v50, v4
	v_mul_f32_e32 v34, v34, v4
	s_waitcnt lgkmcnt(0)
	v_rcp_f32_e32 v147, v2
	v_rcp_f32_e32 v146, v3
	ds_read2_b32 v[2:3], v0 offset0:10 offset1:11
	v_mul_f32_e32 v18, v18, v4
	s_waitcnt lgkmcnt(0)
	v_rcp_f32_e32 v15, v2
	v_rcp_f32_e32 v14, v3
	ds_read2_b32 v[2:3], v0 offset0:16 offset1:17
	s_waitcnt lgkmcnt(0)
	v_rcp_f32_e32 v13, v2
	v_rcp_f32_e32 v12, v3
	ds_read2_b32 v[2:3], v0 offset0:18 offset1:19
	s_waitcnt lgkmcnt(0)
	v_rcp_f32_e32 v11, v2
	v_rcp_f32_e32 v10, v3
	ds_read2_b32 v[2:3], v0 offset0:24 offset1:25
	s_waitcnt lgkmcnt(0)
	v_rcp_f32_e32 v9, v2
	v_rcp_f32_e32 v8, v3
	ds_read2_b32 v[2:3], v0 offset0:26 offset1:27
	s_mul_hi_i32 s3, s83, s1
	s_mul_i32 s2, s83, s1
	s_lshl_b64 s[2:3], s[2:3], 1
	s_waitcnt lgkmcnt(0)
	v_rcp_f32_e32 v7, v2
	v_rcp_f32_e32 v6, v3
	s_add_u32 s56, s0, s2
	s_addc_u32 s57, s4, s3
	s_cmp_gt_u32 s82, 1
	s_cbranch_scc0 .Lep_mode0
	s_add_u32 s58, s80, s6
	s_addc_u32 s59, s81, s7
	s_mul_i32 s2, s83, s1
	s_lshl_b32 s2, s2, 1
	s_add_u32 s58, s58, s2
	s_addc_u32 s59, s59, 0
	v_and_b32_e32 v151, 1, v210
	v_cmp_eq_u32_e64 s[60:61], 0, v151
	v_lshlrev_b32_e32 v2, 2, v210
	global_load_dword v224, v2, s[46:47] offset:0
	global_load_dword v225, v2, s[46:47] offset:128
	global_load_dword v226, v2, s[46:47] offset:256
	global_load_dword v227, v2, s[46:47] offset:384
	global_load_dword v228, v2, s[46:47] offset:512
	global_load_dword v229, v2, s[46:47] offset:640
	global_load_dword v230, v2, s[46:47] offset:768
	global_load_dword v231, v2, s[46:47] offset:896
	v_lshlrev_b32_e32 v3, 12, v237
	v_lshl_add_u32 v3, v210, 4, v3
	global_load_dwordx4 v[152:155], v3, s[56:57] sc1
	v_add_u32_e32 v3, 0x2000, v3
	global_load_dwordx4 v[156:159], v3, s[56:57] sc1
	v_add_u32_e32 v3, 0x2000, v3
	global_load_dwordx4 v[160:163], v3, s[56:57] sc1
	v_add_u32_e32 v3, 0x2000, v3
	global_load_dwordx4 v[164:167], v3, s[56:57] sc1
	v_add_u32_e32 v3, 0x2000, v3
	global_load_dwordx4 v[168:171], v3, s[56:57] sc1
	v_add_u32_e32 v3, 0x2000, v3
	global_load_dwordx4 v[172:175], v3, s[56:57] sc1
	v_add_u32_e32 v3, 0x2000, v3
	global_load_dwordx4 v[176:179], v3, s[56:57] sc1
	v_add_u32_e32 v3, 0x2000, v3
	global_load_dwordx4 v[180:183], v3, s[56:57] sc1
	v_add_u32_e32 v3, 0x2000, v3
	global_load_dwordx4 v[184:187], v3, s[56:57] sc1
	v_add_u32_e32 v3, 0x2000, v3
	global_load_dwordx4 v[188:191], v3, s[56:57] sc1
	v_add_u32_e32 v3, 0x2000, v3
	global_load_dwordx4 v[192:195], v3, s[56:57] sc1
	v_add_u32_e32 v3, 0x2000, v3
	global_load_dwordx4 v[196:199], v3, s[56:57] sc1
	v_add_u32_e32 v3, 0x2000, v3
	global_load_dwordx4 v[200:203], v3, s[56:57] sc1
	v_add_u32_e32 v3, 0x2000, v3
	global_load_dwordx4 v[204:207], v3, s[56:57] sc1
	v_add_u32_e32 v3, 0x2000, v3
	global_load_dwordx4 v[216:219], v3, s[56:57] sc1
	v_add_u32_e32 v3, 0x2000, v3
	global_load_dwordx4 v[220:223], v3, s[56:57] sc1
	v_lshlrev_b32_e32 v212, 2, v210
	v_lshlrev_b32_e32 v213, 7, v237
	v_xad_u32 v0, v212, 64, v213
	v_readlane_b32 s20, v255, 11
	s_nop 3
	s_lshl_b32 s20, s20, 6
	s_add_i32 s20, s20, 0x8000
	v_lshlrev_b32_e32 v212, 12, v237
	v_lshl_add_u32 v212, v210, 4, v212
	v_mul_u32_u24_e32 v213, 62, v151
	v_lshl_add_u32 v208, v210, 1, v213
	v_lshl_add_u32 v208, v237, 11, v208
	v_add_u32_e32 v208, s20, v208
	v_lshlrev_b32_e32 v209, 9, v237
	v_lshl_add_u32 v209, v210, 4, v209
	v_add_u32_e32 v209, s20, v209
	s_waitcnt vmcnt(16)
	v_mul_f32_e32 v224, v236, v224
	v_mul_f32_e32 v225, v236, v225
	v_mul_f32_e32 v226, v236, v226
	v_mul_f32_e32 v227, v236, v227
	v_mul_f32_e32 v228, v236, v228
	v_mul_f32_e32 v229, v236, v229
	v_mul_f32_e32 v230, v236, v230
	v_mul_f32_e32 v231, v236, v231
	s_waitcnt vmcnt(15)
	v_lshlrev_b32_e32 v250, 16, v152
	v_fma_f32 v240, -v17, v130, v250
	v_and_b32_e32 v250, 0xffff0000, v152
	v_fma_f32 v241, -v17, v114, v250
	v_lshlrev_b32_e32 v250, 16, v153
	v_fma_f32 v242, -v17, v98, v250
	v_and_b32_e32 v250, 0xffff0000, v153
	v_fma_f32 v243, -v17, v82, v250
	v_lshlrev_b32_e32 v250, 16, v154
	v_fma_f32 v245, -v17, v66, v250
	v_and_b32_e32 v250, 0xffff0000, v154
	v_fma_f32 v246, -v17, v50, v250
	v_lshlrev_b32_e32 v250, 16, v155
	v_fma_f32 v247, -v17, v34, v250
	v_and_b32_e32 v250, 0xffff0000, v155
	v_fma_f32 v248, -v17, v18, v250
	v_mul_f32_e32 v251, v241, v241
	v_fmac_f32_e32 v251, v240, v240
	v_fmac_f32_e32 v251, v242, v242
	v_fmac_f32_e32 v251, v243, v243
	v_fmac_f32_e32 v251, v245, v245
	v_fmac_f32_e32 v251, v246, v246
	v_fmac_f32_e32 v251, v247, v247
	v_fmac_f32_e32 v251, v248, v248
	s_nop 1
	v_add_f32_dpp v251, v251, v251 quad_perm:[1,0,3,2] row_mask:0xf bank_mask:0xf bound_ctrl:1
	s_nop 1
	v_add_f32_dpp v251, v251, v251 quad_perm:[2,3,0,1] row_mask:0xf bank_mask:0xf bound_ctrl:1
	s_nop 1
	v_add_f32_dpp v251, v251, v251 row_half_mirror row_mask:0xf bank_mask:0xf bound_ctrl:1
	s_nop 1
	v_add_f32_dpp v251, v251, v251 row_mirror row_mask:0xf bank_mask:0xf bound_ctrl:1
	ds_bpermute_b32 v252, v0, v251
	s_waitcnt lgkmcnt(0)
	v_add_f32_e32 v251, v251, v252
	v_fmamk_f32 v251, v251, 0x3b800000, v238
	v_mul_f32_e32 v252, 0x4f800000, v251
	v_cmp_gt_f32_e32 vcc, s24, v251
	s_nop 1
	v_cndmask_b32_e32 v251, v251, v252, vcc
	v_sqrt_f32_e32 v252, v251
	s_nop 0
	v_add_u32_e32 v249, -1, v252
	v_fma_f32 v250, -v249, v252, v251
	v_cmp_ge_f32_e64 s[6:7], 0, v250
	v_add_u32_e32 v250, 1, v252
	s_nop 0
	v_cndmask_b32_e64 v249, v252, v249, s[6:7]
	v_fma_f32 v252, -v250, v252, v251
	v_cmp_lt_f32_e64 s[6:7], 0, v252
	s_nop 1
	v_cndmask_b32_e64 v252, v249, v250, s[6:7]
	v_mul_f32_e32 v249, 0x37800000, v252
	v_cndmask_b32_e32 v252, v252, v249, vcc
	v_cmp_class_f32_e32 vcc, v251, v239
	s_nop 1
	v_cndmask_b32_e32 v251, v252, v251, vcc
	v_div_scale_f32 v252, s[2:3], v251, v251, 1.0
	v_rcp_f32_e32 v249, v252
	s_nop 0
	v_fma_f32 v250, -v252, v249, 1.0
	v_fmac_f32_e32 v249, v250, v249
	v_div_scale_f32 v250, vcc, 1.0, v251, 1.0
	v_mul_f32_e32 v253, v250, v249
	v_fma_f32 v213, -v252, v253, v250
	v_fmac_f32_e32 v253, v213, v249
	v_fma_f32 v252, -v252, v253, v250
	v_div_fmas_f32 v252, v252, v249, v253
	v_div_fixup_f32 v253, v252, v251, 1.0
	v_mul_f32_e32 v240, v240, v253
	v_mul_f32_e32 v241, v241, v253
	v_mul_f32_e32 v242, v242, v253
	v_mul_f32_e32 v243, v243, v253
	v_mul_f32_e32 v245, v245, v253
	v_mul_f32_e32 v246, v246, v253
	v_mul_f32_e32 v247, v247, v253
	v_mul_f32_e32 v248, v248, v253
	v_mul_f32_e32 v240, v224, v240
	v_mul_f32_e32 v241, v225, v241
	v_mul_f32_e32 v242, v226, v242
	v_mul_f32_e32 v243, v227, v243
	v_mul_f32_e32 v245, v228, v245
	v_mul_f32_e32 v246, v229, v246
	v_mul_f32_e32 v247, v230, v247
	v_mul_f32_e32 v248, v231, v248
	v_mov_b32_dpp v232, v240 quad_perm:[1,0,3,2] row_mask:0xf bank_mask:0xf bound_ctrl:1
	v_mov_b32_dpp v233, v241 quad_perm:[1,0,3,2] row_mask:0xf bank_mask:0xf bound_ctrl:1
	v_mov_b32_dpp v234, v242 quad_perm:[1,0,3,2] row_mask:0xf bank_mask:0xf bound_ctrl:1
	v_mov_b32_dpp v235, v243 quad_perm:[1,0,3,2] row_mask:0xf bank_mask:0xf bound_ctrl:1
	v_mov_b32_dpp v2, v245 quad_perm:[1,0,3,2] row_mask:0xf bank_mask:0xf bound_ctrl:1
	v_mov_b32_dpp v3, v246 quad_perm:[1,0,3,2] row_mask:0xf bank_mask:0xf bound_ctrl:1
	v_mov_b32_dpp v5, v247 quad_perm:[1,0,3,2] row_mask:0xf bank_mask:0xf bound_ctrl:1
	v_mov_b32_dpp v151, v248 quad_perm:[1,0,3,2] row_mask:0xf bank_mask:0xf bound_ctrl:1
	v_cvt_pk_bf16_f32 v232, v240, v232
	v_cvt_pk_bf16_f32 v233, v233, v241
	v_cndmask_b32_e64 v232, v233, v232, s[60:61]
	ds_write_b32 v208, v232 offset:0
	v_cvt_pk_bf16_f32 v234, v242, v234
	v_cvt_pk_bf16_f32 v235, v235, v243
	v_cndmask_b32_e64 v234, v235, v234, s[60:61]
	ds_write_b32 v208, v234 offset:128
	v_cvt_pk_bf16_f32 v2, v245, v2
	v_cvt_pk_bf16_f32 v3, v3, v246
	v_cndmask_b32_e64 v2, v3, v2, s[60:61]
	ds_write_b32 v208, v2 offset:256
	v_cvt_pk_bf16_f32 v5, v247, v5
	v_cvt_pk_bf16_f32 v151, v151, v248
	v_cndmask_b32_e64 v5, v151, v5, s[60:61]
	ds_write_b32 v208, v5 offset:384
	s_waitcnt vmcnt(14)
	v_lshlrev_b32_e32 v250, 16, v156
	v_mul_f32_e32 v249, v131, v150
	v_fma_f32 v240, -v17, v249, v250
	v_and_b32_e32 v250, 0xffff0000, v156
	v_mul_f32_e32 v249, v115, v150
	v_fma_f32 v241, -v17, v249, v250
	v_lshlrev_b32_e32 v250, 16, v157
	v_mul_f32_e32 v249, v99, v150
	v_fma_f32 v242, -v17, v249, v250
	v_and_b32_e32 v250, 0xffff0000, v157
	v_mul_f32_e32 v249, v83, v150
	v_fma_f32 v243, -v17, v249, v250
	v_lshlrev_b32_e32 v250, 16, v158
	v_mul_f32_e32 v249, v67, v150
	v_fma_f32 v245, -v17, v249, v250
	v_and_b32_e32 v250, 0xffff0000, v158
	v_mul_f32_e32 v249, v51, v150
	v_fma_f32 v246, -v17, v249, v250
	v_lshlrev_b32_e32 v250, 16, v159
	v_mul_f32_e32 v249, v35, v150
	v_fma_f32 v247, -v17, v249, v250
	v_and_b32_e32 v250, 0xffff0000, v159
	v_mul_f32_e32 v249, v19, v150
	v_fma_f32 v248, -v17, v249, v250
	v_mul_f32_e32 v251, v241, v241
	v_fmac_f32_e32 v251, v240, v240
	v_fmac_f32_e32 v251, v242, v242
	v_fmac_f32_e32 v251, v243, v243
	v_fmac_f32_e32 v251, v245, v245
	v_fmac_f32_e32 v251, v246, v246
	v_fmac_f32_e32 v251, v247, v247
	v_fmac_f32_e32 v251, v248, v248
	s_nop 1
	v_add_f32_dpp v251, v251, v251 quad_perm:[1,0,3,2] row_mask:0xf bank_mask:0xf bound_ctrl:1
	s_nop 1
	v_add_f32_dpp v251, v251, v251 quad_perm:[2,3,0,1] row_mask:0xf bank_mask:0xf bound_ctrl:1
	s_nop 1
	v_add_f32_dpp v251, v251, v251 row_half_mirror row_mask:0xf bank_mask:0xf bound_ctrl:1
	s_nop 1
	v_add_f32_dpp v251, v251, v251 row_mirror row_mask:0xf bank_mask:0xf bound_ctrl:1
	ds_bpermute_b32 v252, v0, v251
	s_waitcnt lgkmcnt(0)
	v_add_f32_e32 v251, v251, v252
	v_fmamk_f32 v251, v251, 0x3b800000, v238
	v_mul_f32_e32 v252, 0x4f800000, v251
	v_cmp_gt_f32_e32 vcc, s24, v251
	s_nop 1
	v_cndmask_b32_e32 v251, v251, v252, vcc
	v_sqrt_f32_e32 v252, v251
	s_nop 0
	v_add_u32_e32 v249, -1, v252
	v_fma_f32 v250, -v249, v252, v251
	v_cmp_ge_f32_e64 s[6:7], 0, v250
	v_add_u32_e32 v250, 1, v252
	s_nop 0
	v_cndmask_b32_e64 v249, v252, v249, s[6:7]
	v_fma_f32 v252, -v250, v252, v251
	v_cmp_lt_f32_e64 s[6:7], 0, v252
	s_nop 1
	v_cndmask_b32_e64 v252, v249, v250, s[6:7]
	v_mul_f32_e32 v249, 0x37800000, v252
	v_cndmask_b32_e32 v252, v252, v249, vcc
	v_cmp_class_f32_e32 vcc, v251, v239
	s_nop 1
	v_cndmask_b32_e32 v251, v252, v251, vcc
	v_div_scale_f32 v252, s[2:3], v251, v251, 1.0
	v_rcp_f32_e32 v249, v252
	s_nop 0
	v_fma_f32 v250, -v252, v249, 1.0
	v_fmac_f32_e32 v249, v250, v249
	v_div_scale_f32 v250, vcc, 1.0, v251, 1.0
	v_mul_f32_e32 v253, v250, v249
	v_fma_f32 v213, -v252, v253, v250
	v_fmac_f32_e32 v253, v213, v249
	v_fma_f32 v252, -v252, v253, v250
	v_div_fmas_f32 v252, v252, v249, v253
	v_div_fixup_f32 v253, v252, v251, 1.0
	v_mul_f32_e32 v240, v240, v253
	v_mul_f32_e32 v241, v241, v253
	v_mul_f32_e32 v242, v242, v253
	v_mul_f32_e32 v243, v243, v253
	v_mul_f32_e32 v245, v245, v253
	v_mul_f32_e32 v246, v246, v253
	v_mul_f32_e32 v247, v247, v253
	v_mul_f32_e32 v248, v248, v253
	v_mul_f32_e32 v240, v224, v240
	v_mul_f32_e32 v241, v225, v241
	v_mul_f32_e32 v242, v226, v242
	v_mul_f32_e32 v243, v227, v243
	v_mul_f32_e32 v245, v228, v245
	v_mul_f32_e32 v246, v229, v246
	v_mul_f32_e32 v247, v230, v247
	v_mul_f32_e32 v248, v231, v248
	v_mov_b32_dpp v232, v240 quad_perm:[1,0,3,2] row_mask:0xf bank_mask:0xf bound_ctrl:1
	v_mov_b32_dpp v233, v241 quad_perm:[1,0,3,2] row_mask:0xf bank_mask:0xf bound_ctrl:1
	v_mov_b32_dpp v234, v242 quad_perm:[1,0,3,2] row_mask:0xf bank_mask:0xf bound_ctrl:1
	v_mov_b32_dpp v235, v243 quad_perm:[1,0,3,2] row_mask:0xf bank_mask:0xf bound_ctrl:1
	v_mov_b32_dpp v2, v245 quad_perm:[1,0,3,2] row_mask:0xf bank_mask:0xf bound_ctrl:1
	v_mov_b32_dpp v3, v246 quad_perm:[1,0,3,2] row_mask:0xf bank_mask:0xf bound_ctrl:1
	v_mov_b32_dpp v5, v247 quad_perm:[1,0,3,2] row_mask:0xf bank_mask:0xf bound_ctrl:1
	v_mov_b32_dpp v151, v248 quad_perm:[1,0,3,2] row_mask:0xf bank_mask:0xf bound_ctrl:1
	v_cvt_pk_bf16_f32 v232, v240, v232
	v_cvt_pk_bf16_f32 v233, v233, v241
	v_cndmask_b32_e64 v232, v233, v232, s[60:61]
	ds_write_b32 v208, v232 offset:512
	v_cvt_pk_bf16_f32 v234, v242, v234
	v_cvt_pk_bf16_f32 v235, v235, v243
	v_cndmask_b32_e64 v234, v235, v234, s[60:61]
	ds_write_b32 v208, v234 offset:640
	v_cvt_pk_bf16_f32 v2, v245, v2
	v_cvt_pk_bf16_f32 v3, v3, v246
	v_cndmask_b32_e64 v2, v3, v2, s[60:61]
	ds_write_b32 v208, v2 offset:768
	v_cvt_pk_bf16_f32 v5, v247, v5
	v_cvt_pk_bf16_f32 v151, v151, v248
	v_cndmask_b32_e64 v5, v151, v5, s[60:61]
	ds_write_b32 v208, v5 offset:896
	s_waitcnt vmcnt(13)
	v_lshlrev_b32_e32 v250, 16, v160
	v_mul_f32_e32 v249, v132, v149
	v_fma_f32 v240, -v17, v249, v250
	v_and_b32_e32 v250, 0xffff0000, v160
	v_mul_f32_e32 v249, v116, v149
	v_fma_f32 v241, -v17, v249, v250
	v_lshlrev_b32_e32 v250, 16, v161
	v_mul_f32_e32 v249, v100, v149
	v_fma_f32 v242, -v17, v249, v250
	v_and_b32_e32 v250, 0xffff0000, v161
	v_mul_f32_e32 v249, v84, v149
	v_fma_f32 v243, -v17, v249, v250
	v_lshlrev_b32_e32 v250, 16, v162
	v_mul_f32_e32 v249, v68, v149
	v_fma_f32 v245, -v17, v249, v250
	v_and_b32_e32 v250, 0xffff0000, v162
	v_mul_f32_e32 v249, v52, v149
	v_fma_f32 v246, -v17, v249, v250
	v_lshlrev_b32_e32 v250, 16, v163
	v_mul_f32_e32 v249, v36, v149
	v_fma_f32 v247, -v17, v249, v250
	v_and_b32_e32 v250, 0xffff0000, v163
	v_mul_f32_e32 v249, v20, v149
	v_fma_f32 v248, -v17, v249, v250
	v_mul_f32_e32 v251, v241, v241
	v_fmac_f32_e32 v251, v240, v240
	v_fmac_f32_e32 v251, v242, v242
	v_fmac_f32_e32 v251, v243, v243
	v_fmac_f32_e32 v251, v245, v245
	v_fmac_f32_e32 v251, v246, v246
	v_fmac_f32_e32 v251, v247, v247
	v_fmac_f32_e32 v251, v248, v248
	s_nop 1
	v_add_f32_dpp v251, v251, v251 quad_perm:[1,0,3,2] row_mask:0xf bank_mask:0xf bound_ctrl:1
	s_nop 1
	v_add_f32_dpp v251, v251, v251 quad_perm:[2,3,0,1] row_mask:0xf bank_mask:0xf bound_ctrl:1
	s_nop 1
	v_add_f32_dpp v251, v251, v251 row_half_mirror row_mask:0xf bank_mask:0xf bound_ctrl:1
	s_nop 1
	v_add_f32_dpp v251, v251, v251 row_mirror row_mask:0xf bank_mask:0xf bound_ctrl:1
	ds_bpermute_b32 v252, v0, v251
	s_waitcnt lgkmcnt(0)
	v_add_f32_e32 v251, v251, v252
	v_fmamk_f32 v251, v251, 0x3b800000, v238
	v_mul_f32_e32 v252, 0x4f800000, v251
	v_cmp_gt_f32_e32 vcc, s24, v251
	s_nop 1
	v_cndmask_b32_e32 v251, v251, v252, vcc
	v_sqrt_f32_e32 v252, v251
	s_nop 0
	v_add_u32_e32 v249, -1, v252
	v_fma_f32 v250, -v249, v252, v251
	v_cmp_ge_f32_e64 s[6:7], 0, v250
	v_add_u32_e32 v250, 1, v252
	s_nop 0
	v_cndmask_b32_e64 v249, v252, v249, s[6:7]
	v_fma_f32 v252, -v250, v252, v251
	v_cmp_lt_f32_e64 s[6:7], 0, v252
	s_nop 1
	v_cndmask_b32_e64 v252, v249, v250, s[6:7]
	v_mul_f32_e32 v249, 0x37800000, v252
	v_cndmask_b32_e32 v252, v252, v249, vcc
	v_cmp_class_f32_e32 vcc, v251, v239
	s_nop 1
	v_cndmask_b32_e32 v251, v252, v251, vcc
	v_div_scale_f32 v252, s[2:3], v251, v251, 1.0
	v_rcp_f32_e32 v249, v252
	s_nop 0
	v_fma_f32 v250, -v252, v249, 1.0
	v_fmac_f32_e32 v249, v250, v249
	v_div_scale_f32 v250, vcc, 1.0, v251, 1.0
	v_mul_f32_e32 v253, v250, v249
	v_fma_f32 v213, -v252, v253, v250
	v_fmac_f32_e32 v253, v213, v249
	v_fma_f32 v252, -v252, v253, v250
	v_div_fmas_f32 v252, v252, v249, v253
	v_div_fixup_f32 v253, v252, v251, 1.0
	v_mul_f32_e32 v240, v240, v253
	v_mul_f32_e32 v241, v241, v253
	v_mul_f32_e32 v242, v242, v253
	v_mul_f32_e32 v243, v243, v253
	v_mul_f32_e32 v245, v245, v253
	v_mul_f32_e32 v246, v246, v253
	v_mul_f32_e32 v247, v247, v253
	v_mul_f32_e32 v248, v248, v253
	v_mul_f32_e32 v240, v224, v240
	v_mul_f32_e32 v241, v225, v241
	v_mul_f32_e32 v242, v226, v242
	v_mul_f32_e32 v243, v227, v243
	v_mul_f32_e32 v245, v228, v245
	v_mul_f32_e32 v246, v229, v246
	v_mul_f32_e32 v247, v230, v247
	v_mul_f32_e32 v248, v231, v248
	v_mov_b32_dpp v232, v240 quad_perm:[1,0,3,2] row_mask:0xf bank_mask:0xf bound_ctrl:1
	v_mov_b32_dpp v233, v241 quad_perm:[1,0,3,2] row_mask:0xf bank_mask:0xf bound_ctrl:1
	v_mov_b32_dpp v234, v242 quad_perm:[1,0,3,2] row_mask:0xf bank_mask:0xf bound_ctrl:1
	v_mov_b32_dpp v235, v243 quad_perm:[1,0,3,2] row_mask:0xf bank_mask:0xf bound_ctrl:1
	v_mov_b32_dpp v2, v245 quad_perm:[1,0,3,2] row_mask:0xf bank_mask:0xf bound_ctrl:1
	v_mov_b32_dpp v3, v246 quad_perm:[1,0,3,2] row_mask:0xf bank_mask:0xf bound_ctrl:1
	v_mov_b32_dpp v5, v247 quad_perm:[1,0,3,2] row_mask:0xf bank_mask:0xf bound_ctrl:1
	v_mov_b32_dpp v151, v248 quad_perm:[1,0,3,2] row_mask:0xf bank_mask:0xf bound_ctrl:1
	v_cvt_pk_bf16_f32 v232, v240, v232
	v_cvt_pk_bf16_f32 v233, v233, v241
	v_cndmask_b32_e64 v232, v233, v232, s[60:61]
	ds_write_b32 v208, v232 offset:1024
	v_cvt_pk_bf16_f32 v234, v242, v234
	v_cvt_pk_bf16_f32 v235, v235, v243
	v_cndmask_b32_e64 v234, v235, v234, s[60:61]
	ds_write_b32 v208, v234 offset:1152
	v_cvt_pk_bf16_f32 v2, v245, v2
	v_cvt_pk_bf16_f32 v3, v3, v246
	v_cndmask_b32_e64 v2, v3, v2, s[60:61]
	ds_write_b32 v208, v2 offset:1280
	v_cvt_pk_bf16_f32 v5, v247, v5
	v_cvt_pk_bf16_f32 v151, v151, v248
	v_cndmask_b32_e64 v5, v151, v5, s[60:61]
	ds_write_b32 v208, v5 offset:1408
	s_waitcnt vmcnt(12)
	v_lshlrev_b32_e32 v250, 16, v164
	v_mul_f32_e32 v249, v133, v148
	v_fma_f32 v240, -v17, v249, v250
	v_and_b32_e32 v250, 0xffff0000, v164
	v_mul_f32_e32 v249, v117, v148
	v_fma_f32 v241, -v17, v249, v250
	v_lshlrev_b32_e32 v250, 16, v165
	v_mul_f32_e32 v249, v101, v148
	v_fma_f32 v242, -v17, v249, v250
	v_and_b32_e32 v250, 0xffff0000, v165
	v_mul_f32_e32 v249, v85, v148
	v_fma_f32 v243, -v17, v249, v250
	v_lshlrev_b32_e32 v250, 16, v166
	v_mul_f32_e32 v249, v69, v148
	v_fma_f32 v245, -v17, v249, v250
	v_and_b32_e32 v250, 0xffff0000, v166
	v_mul_f32_e32 v249, v53, v148
	v_fma_f32 v246, -v17, v249, v250
	v_lshlrev_b32_e32 v250, 16, v167
	v_mul_f32_e32 v249, v37, v148
	v_fma_f32 v247, -v17, v249, v250
	v_and_b32_e32 v250, 0xffff0000, v167
	v_mul_f32_e32 v249, v21, v148
	v_fma_f32 v248, -v17, v249, v250
	v_mul_f32_e32 v251, v241, v241
	v_fmac_f32_e32 v251, v240, v240
	v_fmac_f32_e32 v251, v242, v242
	v_fmac_f32_e32 v251, v243, v243
	v_fmac_f32_e32 v251, v245, v245
	v_fmac_f32_e32 v251, v246, v246
	v_fmac_f32_e32 v251, v247, v247
	v_fmac_f32_e32 v251, v248, v248
	s_nop 1
	v_add_f32_dpp v251, v251, v251 quad_perm:[1,0,3,2] row_mask:0xf bank_mask:0xf bound_ctrl:1
	s_nop 1
	v_add_f32_dpp v251, v251, v251 quad_perm:[2,3,0,1] row_mask:0xf bank_mask:0xf bound_ctrl:1
	s_nop 1
	v_add_f32_dpp v251, v251, v251 row_half_mirror row_mask:0xf bank_mask:0xf bound_ctrl:1
	s_nop 1
	v_add_f32_dpp v251, v251, v251 row_mirror row_mask:0xf bank_mask:0xf bound_ctrl:1
	ds_bpermute_b32 v252, v0, v251
	s_waitcnt lgkmcnt(0)
	v_add_f32_e32 v251, v251, v252
	v_fmamk_f32 v251, v251, 0x3b800000, v238
	v_mul_f32_e32 v252, 0x4f800000, v251
	v_cmp_gt_f32_e32 vcc, s24, v251
	s_nop 1
	v_cndmask_b32_e32 v251, v251, v252, vcc
	v_sqrt_f32_e32 v252, v251
	s_nop 0
	v_add_u32_e32 v249, -1, v252
	v_fma_f32 v250, -v249, v252, v251
	v_cmp_ge_f32_e64 s[6:7], 0, v250
	v_add_u32_e32 v250, 1, v252
	s_nop 0
	v_cndmask_b32_e64 v249, v252, v249, s[6:7]
	v_fma_f32 v252, -v250, v252, v251
	v_cmp_lt_f32_e64 s[6:7], 0, v252
	s_nop 1
	v_cndmask_b32_e64 v252, v249, v250, s[6:7]
	v_mul_f32_e32 v249, 0x37800000, v252
	v_cndmask_b32_e32 v252, v252, v249, vcc
	v_cmp_class_f32_e32 vcc, v251, v239
	s_nop 1
	v_cndmask_b32_e32 v251, v252, v251, vcc
	v_div_scale_f32 v252, s[2:3], v251, v251, 1.0
	v_rcp_f32_e32 v249, v252
	s_nop 0
	v_fma_f32 v250, -v252, v249, 1.0
	v_fmac_f32_e32 v249, v250, v249
	v_div_scale_f32 v250, vcc, 1.0, v251, 1.0
	v_mul_f32_e32 v253, v250, v249
	v_fma_f32 v213, -v252, v253, v250
	v_fmac_f32_e32 v253, v213, v249
	v_fma_f32 v252, -v252, v253, v250
	v_div_fmas_f32 v252, v252, v249, v253
	v_div_fixup_f32 v253, v252, v251, 1.0
	v_mul_f32_e32 v240, v240, v253
	v_mul_f32_e32 v241, v241, v253
	v_mul_f32_e32 v242, v242, v253
	v_mul_f32_e32 v243, v243, v253
	v_mul_f32_e32 v245, v245, v253
	v_mul_f32_e32 v246, v246, v253
	v_mul_f32_e32 v247, v247, v253
	v_mul_f32_e32 v248, v248, v253
	v_mul_f32_e32 v240, v224, v240
	v_mul_f32_e32 v241, v225, v241
	v_mul_f32_e32 v242, v226, v242
	v_mul_f32_e32 v243, v227, v243
	v_mul_f32_e32 v245, v228, v245
	v_mul_f32_e32 v246, v229, v246
	v_mul_f32_e32 v247, v230, v247
	v_mul_f32_e32 v248, v231, v248
	v_mov_b32_dpp v232, v240 quad_perm:[1,0,3,2] row_mask:0xf bank_mask:0xf bound_ctrl:1
	v_mov_b32_dpp v233, v241 quad_perm:[1,0,3,2] row_mask:0xf bank_mask:0xf bound_ctrl:1
	v_mov_b32_dpp v234, v242 quad_perm:[1,0,3,2] row_mask:0xf bank_mask:0xf bound_ctrl:1
	v_mov_b32_dpp v235, v243 quad_perm:[1,0,3,2] row_mask:0xf bank_mask:0xf bound_ctrl:1
	v_mov_b32_dpp v2, v245 quad_perm:[1,0,3,2] row_mask:0xf bank_mask:0xf bound_ctrl:1
	v_mov_b32_dpp v3, v246 quad_perm:[1,0,3,2] row_mask:0xf bank_mask:0xf bound_ctrl:1
	v_mov_b32_dpp v5, v247 quad_perm:[1,0,3,2] row_mask:0xf bank_mask:0xf bound_ctrl:1
	v_mov_b32_dpp v151, v248 quad_perm:[1,0,3,2] row_mask:0xf bank_mask:0xf bound_ctrl:1
	v_cvt_pk_bf16_f32 v232, v240, v232
	v_cvt_pk_bf16_f32 v233, v233, v241
	v_cndmask_b32_e64 v232, v233, v232, s[60:61]
	ds_write_b32 v208, v232 offset:1536
	v_cvt_pk_bf16_f32 v234, v242, v234
	v_cvt_pk_bf16_f32 v235, v235, v243
	v_cndmask_b32_e64 v234, v235, v234, s[60:61]
	ds_write_b32 v208, v234 offset:1664
	v_cvt_pk_bf16_f32 v2, v245, v2
	v_cvt_pk_bf16_f32 v3, v3, v246
	v_cndmask_b32_e64 v2, v3, v2, s[60:61]
	ds_write_b32 v208, v2 offset:1792
	v_cvt_pk_bf16_f32 v5, v247, v5
	v_cvt_pk_bf16_f32 v151, v151, v248
	v_cndmask_b32_e64 v5, v151, v5, s[60:61]
	ds_write_b32 v208, v5 offset:1920
	ds_read_b128 v[152:155], v209 offset:0
	ds_read_b128 v[156:159], v209 offset:1024
	ds_read_b128 v[160:163], v209 offset:2048
	ds_read_b128 v[164:167], v209 offset:3072
	s_waitcnt lgkmcnt(3)
	v_add_u32_e32 v249, 0x0, v212
	global_store_dwordx4 v249, v[152:155], s[58:59] sc1
	s_waitcnt lgkmcnt(2)
	v_add_u32_e32 v249, 0x2000, v212
	global_store_dwordx4 v249, v[156:159], s[58:59] sc1
	s_waitcnt lgkmcnt(1)
	v_add_u32_e32 v249, 0x4000, v212
	global_store_dwordx4 v249, v[160:163], s[58:59] sc1
	s_waitcnt lgkmcnt(0)
	v_add_u32_e32 v249, 0x6000, v212
	global_store_dwordx4 v249, v[164:167], s[58:59] sc1
	s_waitcnt vmcnt(15)
	v_lshlrev_b32_e32 v250, 16, v168
	v_mul_f32_e32 v249, v134, v147
	v_fma_f32 v240, -v17, v249, v250
	v_and_b32_e32 v250, 0xffff0000, v168
	v_mul_f32_e32 v249, v118, v147
	v_fma_f32 v241, -v17, v249, v250
	v_lshlrev_b32_e32 v250, 16, v169
	v_mul_f32_e32 v249, v102, v147
	v_fma_f32 v242, -v17, v249, v250
	v_and_b32_e32 v250, 0xffff0000, v169
	v_mul_f32_e32 v249, v86, v147
	v_fma_f32 v243, -v17, v249, v250
	v_lshlrev_b32_e32 v250, 16, v170
	v_mul_f32_e32 v249, v70, v147
	v_fma_f32 v245, -v17, v249, v250
	v_and_b32_e32 v250, 0xffff0000, v170
	v_mul_f32_e32 v249, v54, v147
	v_fma_f32 v246, -v17, v249, v250
	v_lshlrev_b32_e32 v250, 16, v171
	v_mul_f32_e32 v249, v38, v147
	v_fma_f32 v247, -v17, v249, v250
	v_and_b32_e32 v250, 0xffff0000, v171
	v_mul_f32_e32 v249, v22, v147
	v_fma_f32 v248, -v17, v249, v250
	v_mul_f32_e32 v251, v241, v241
	v_fmac_f32_e32 v251, v240, v240
	v_fmac_f32_e32 v251, v242, v242
	v_fmac_f32_e32 v251, v243, v243
	v_fmac_f32_e32 v251, v245, v245
	v_fmac_f32_e32 v251, v246, v246
	v_fmac_f32_e32 v251, v247, v247
	v_fmac_f32_e32 v251, v248, v248
	s_nop 1
	v_add_f32_dpp v251, v251, v251 quad_perm:[1,0,3,2] row_mask:0xf bank_mask:0xf bound_ctrl:1
	s_nop 1
	v_add_f32_dpp v251, v251, v251 quad_perm:[2,3,0,1] row_mask:0xf bank_mask:0xf bound_ctrl:1
	s_nop 1
	v_add_f32_dpp v251, v251, v251 row_half_mirror row_mask:0xf bank_mask:0xf bound_ctrl:1
	s_nop 1
	v_add_f32_dpp v251, v251, v251 row_mirror row_mask:0xf bank_mask:0xf bound_ctrl:1
	ds_bpermute_b32 v252, v0, v251
	s_waitcnt lgkmcnt(0)
	v_add_f32_e32 v251, v251, v252
	v_fmamk_f32 v251, v251, 0x3b800000, v238
	v_mul_f32_e32 v252, 0x4f800000, v251
	v_cmp_gt_f32_e32 vcc, s24, v251
	s_nop 1
	v_cndmask_b32_e32 v251, v251, v252, vcc
	v_sqrt_f32_e32 v252, v251
	s_nop 0
	v_add_u32_e32 v249, -1, v252
	v_fma_f32 v250, -v249, v252, v251
	v_cmp_ge_f32_e64 s[6:7], 0, v250
	v_add_u32_e32 v250, 1, v252
	s_nop 0
	v_cndmask_b32_e64 v249, v252, v249, s[6:7]
	v_fma_f32 v252, -v250, v252, v251
	v_cmp_lt_f32_e64 s[6:7], 0, v252
	s_nop 1
	v_cndmask_b32_e64 v252, v249, v250, s[6:7]
	v_mul_f32_e32 v249, 0x37800000, v252
	v_cndmask_b32_e32 v252, v252, v249, vcc
	v_cmp_class_f32_e32 vcc, v251, v239
	s_nop 1
	v_cndmask_b32_e32 v251, v252, v251, vcc
	v_div_scale_f32 v252, s[2:3], v251, v251, 1.0
	v_rcp_f32_e32 v249, v252
	s_nop 0
	v_fma_f32 v250, -v252, v249, 1.0
	v_fmac_f32_e32 v249, v250, v249
	v_div_scale_f32 v250, vcc, 1.0, v251, 1.0
	v_mul_f32_e32 v253, v250, v249
	v_fma_f32 v213, -v252, v253, v250
	v_fmac_f32_e32 v253, v213, v249
	v_fma_f32 v252, -v252, v253, v250
	v_div_fmas_f32 v252, v252, v249, v253
	v_div_fixup_f32 v253, v252, v251, 1.0
	v_mul_f32_e32 v240, v240, v253
	v_mul_f32_e32 v241, v241, v253
	v_mul_f32_e32 v242, v242, v253
	v_mul_f32_e32 v243, v243, v253
	v_mul_f32_e32 v245, v245, v253
	v_mul_f32_e32 v246, v246, v253
	v_mul_f32_e32 v247, v247, v253
	v_mul_f32_e32 v248, v248, v253
	v_mul_f32_e32 v240, v224, v240
	v_mul_f32_e32 v241, v225, v241
	v_mul_f32_e32 v242, v226, v242
	v_mul_f32_e32 v243, v227, v243
	v_mul_f32_e32 v245, v228, v245
	v_mul_f32_e32 v246, v229, v246
	v_mul_f32_e32 v247, v230, v247
	v_mul_f32_e32 v248, v231, v248
	v_mov_b32_dpp v232, v240 quad_perm:[1,0,3,2] row_mask:0xf bank_mask:0xf bound_ctrl:1
	v_mov_b32_dpp v233, v241 quad_perm:[1,0,3,2] row_mask:0xf bank_mask:0xf bound_ctrl:1
	v_mov_b32_dpp v234, v242 quad_perm:[1,0,3,2] row_mask:0xf bank_mask:0xf bound_ctrl:1
	v_mov_b32_dpp v235, v243 quad_perm:[1,0,3,2] row_mask:0xf bank_mask:0xf bound_ctrl:1
	v_mov_b32_dpp v2, v245 quad_perm:[1,0,3,2] row_mask:0xf bank_mask:0xf bound_ctrl:1
	v_mov_b32_dpp v3, v246 quad_perm:[1,0,3,2] row_mask:0xf bank_mask:0xf bound_ctrl:1
	v_mov_b32_dpp v5, v247 quad_perm:[1,0,3,2] row_mask:0xf bank_mask:0xf bound_ctrl:1
	v_mov_b32_dpp v151, v248 quad_perm:[1,0,3,2] row_mask:0xf bank_mask:0xf bound_ctrl:1
	v_cvt_pk_bf16_f32 v232, v240, v232
	v_cvt_pk_bf16_f32 v233, v233, v241
	v_cndmask_b32_e64 v232, v233, v232, s[60:61]
	ds_write_b32 v208, v232 offset:0
	v_cvt_pk_bf16_f32 v234, v242, v234
	v_cvt_pk_bf16_f32 v235, v235, v243
	v_cndmask_b32_e64 v234, v235, v234, s[60:61]
	ds_write_b32 v208, v234 offset:128
	v_cvt_pk_bf16_f32 v2, v245, v2
	v_cvt_pk_bf16_f32 v3, v3, v246
	v_cndmask_b32_e64 v2, v3, v2, s[60:61]
	ds_write_b32 v208, v2 offset:256
	v_cvt_pk_bf16_f32 v5, v247, v5
	v_cvt_pk_bf16_f32 v151, v151, v248
	v_cndmask_b32_e64 v5, v151, v5, s[60:61]
	ds_write_b32 v208, v5 offset:384
	s_waitcnt vmcnt(14)
	v_lshlrev_b32_e32 v250, 16, v172
	v_mul_f32_e32 v249, v135, v146
	v_fma_f32 v240, -v17, v249, v250
	v_and_b32_e32 v250, 0xffff0000, v172
	v_mul_f32_e32 v249, v119, v146
	v_fma_f32 v241, -v17, v249, v250
	v_lshlrev_b32_e32 v250, 16, v173
	v_mul_f32_e32 v249, v103, v146
	v_fma_f32 v242, -v17, v249, v250
	v_and_b32_e32 v250, 0xffff0000, v173
	v_mul_f32_e32 v249, v87, v146
	v_fma_f32 v243, -v17, v249, v250
	v_lshlrev_b32_e32 v250, 16, v174
	v_mul_f32_e32 v249, v71, v146
	v_fma_f32 v245, -v17, v249, v250
	v_and_b32_e32 v250, 0xffff0000, v174
	v_mul_f32_e32 v249, v55, v146
	v_fma_f32 v246, -v17, v249, v250
	v_lshlrev_b32_e32 v250, 16, v175
	v_mul_f32_e32 v249, v39, v146
	v_fma_f32 v247, -v17, v249, v250
	v_and_b32_e32 v250, 0xffff0000, v175
	v_mul_f32_e32 v249, v23, v146
	v_fma_f32 v248, -v17, v249, v250
	v_mul_f32_e32 v251, v241, v241
	v_fmac_f32_e32 v251, v240, v240
	v_fmac_f32_e32 v251, v242, v242
	v_fmac_f32_e32 v251, v243, v243
	v_fmac_f32_e32 v251, v245, v245
	v_fmac_f32_e32 v251, v246, v246
	v_fmac_f32_e32 v251, v247, v247
	v_fmac_f32_e32 v251, v248, v248
	s_nop 1
	v_add_f32_dpp v251, v251, v251 quad_perm:[1,0,3,2] row_mask:0xf bank_mask:0xf bound_ctrl:1
	s_nop 1
	v_add_f32_dpp v251, v251, v251 quad_perm:[2,3,0,1] row_mask:0xf bank_mask:0xf bound_ctrl:1
	s_nop 1
	v_add_f32_dpp v251, v251, v251 row_half_mirror row_mask:0xf bank_mask:0xf bound_ctrl:1
	s_nop 1
	v_add_f32_dpp v251, v251, v251 row_mirror row_mask:0xf bank_mask:0xf bound_ctrl:1
	ds_bpermute_b32 v252, v0, v251
	s_waitcnt lgkmcnt(0)
	v_add_f32_e32 v251, v251, v252
	v_fmamk_f32 v251, v251, 0x3b800000, v238
	v_mul_f32_e32 v252, 0x4f800000, v251
	v_cmp_gt_f32_e32 vcc, s24, v251
	s_nop 1
	v_cndmask_b32_e32 v251, v251, v252, vcc
	v_sqrt_f32_e32 v252, v251
	s_nop 0
	v_add_u32_e32 v249, -1, v252
	v_fma_f32 v250, -v249, v252, v251
	v_cmp_ge_f32_e64 s[6:7], 0, v250
	v_add_u32_e32 v250, 1, v252
	s_nop 0
	v_cndmask_b32_e64 v249, v252, v249, s[6:7]
	v_fma_f32 v252, -v250, v252, v251
	v_cmp_lt_f32_e64 s[6:7], 0, v252
	s_nop 1
	v_cndmask_b32_e64 v252, v249, v250, s[6:7]
	v_mul_f32_e32 v249, 0x37800000, v252
	v_cndmask_b32_e32 v252, v252, v249, vcc
	v_cmp_class_f32_e32 vcc, v251, v239
	s_nop 1
	v_cndmask_b32_e32 v251, v252, v251, vcc
	v_div_scale_f32 v252, s[2:3], v251, v251, 1.0
	v_rcp_f32_e32 v249, v252
	s_nop 0
	v_fma_f32 v250, -v252, v249, 1.0
	v_fmac_f32_e32 v249, v250, v249
	v_div_scale_f32 v250, vcc, 1.0, v251, 1.0
	v_mul_f32_e32 v253, v250, v249
	v_fma_f32 v213, -v252, v253, v250
	v_fmac_f32_e32 v253, v213, v249
	v_fma_f32 v252, -v252, v253, v250
	v_div_fmas_f32 v252, v252, v249, v253
	v_div_fixup_f32 v253, v252, v251, 1.0
	v_mul_f32_e32 v240, v240, v253
	v_mul_f32_e32 v241, v241, v253
	v_mul_f32_e32 v242, v242, v253
	v_mul_f32_e32 v243, v243, v253
	v_mul_f32_e32 v245, v245, v253
	v_mul_f32_e32 v246, v246, v253
	v_mul_f32_e32 v247, v247, v253
	v_mul_f32_e32 v248, v248, v253
	v_mul_f32_e32 v240, v224, v240
	v_mul_f32_e32 v241, v225, v241
	v_mul_f32_e32 v242, v226, v242
	v_mul_f32_e32 v243, v227, v243
	v_mul_f32_e32 v245, v228, v245
	v_mul_f32_e32 v246, v229, v246
	v_mul_f32_e32 v247, v230, v247
	v_mul_f32_e32 v248, v231, v248
	v_mov_b32_dpp v232, v240 quad_perm:[1,0,3,2] row_mask:0xf bank_mask:0xf bound_ctrl:1
	v_mov_b32_dpp v233, v241 quad_perm:[1,0,3,2] row_mask:0xf bank_mask:0xf bound_ctrl:1
	v_mov_b32_dpp v234, v242 quad_perm:[1,0,3,2] row_mask:0xf bank_mask:0xf bound_ctrl:1
	v_mov_b32_dpp v235, v243 quad_perm:[1,0,3,2] row_mask:0xf bank_mask:0xf bound_ctrl:1
	v_mov_b32_dpp v2, v245 quad_perm:[1,0,3,2] row_mask:0xf bank_mask:0xf bound_ctrl:1
	v_mov_b32_dpp v3, v246 quad_perm:[1,0,3,2] row_mask:0xf bank_mask:0xf bound_ctrl:1
	v_mov_b32_dpp v5, v247 quad_perm:[1,0,3,2] row_mask:0xf bank_mask:0xf bound_ctrl:1
	v_mov_b32_dpp v151, v248 quad_perm:[1,0,3,2] row_mask:0xf bank_mask:0xf bound_ctrl:1
	v_cvt_pk_bf16_f32 v232, v240, v232
	v_cvt_pk_bf16_f32 v233, v233, v241
	v_cndmask_b32_e64 v232, v233, v232, s[60:61]
	ds_write_b32 v208, v232 offset:512
	v_cvt_pk_bf16_f32 v234, v242, v234
	v_cvt_pk_bf16_f32 v235, v235, v243
	v_cndmask_b32_e64 v234, v235, v234, s[60:61]
	ds_write_b32 v208, v234 offset:640
	v_cvt_pk_bf16_f32 v2, v245, v2
	v_cvt_pk_bf16_f32 v3, v3, v246
	v_cndmask_b32_e64 v2, v3, v2, s[60:61]
	ds_write_b32 v208, v2 offset:768
	v_cvt_pk_bf16_f32 v5, v247, v5
	v_cvt_pk_bf16_f32 v151, v151, v248
	v_cndmask_b32_e64 v5, v151, v5, s[60:61]
	ds_write_b32 v208, v5 offset:896
	s_waitcnt vmcnt(13)
	v_lshlrev_b32_e32 v250, 16, v176
	v_mul_f32_e32 v249, v136, v15
	v_fma_f32 v240, -v17, v249, v250
	v_and_b32_e32 v250, 0xffff0000, v176
	v_mul_f32_e32 v249, v120, v15
	v_fma_f32 v241, -v17, v249, v250
	v_lshlrev_b32_e32 v250, 16, v177
	v_mul_f32_e32 v249, v104, v15
	v_fma_f32 v242, -v17, v249, v250
	v_and_b32_e32 v250, 0xffff0000, v177
	v_mul_f32_e32 v249, v88, v15
	v_fma_f32 v243, -v17, v249, v250
	v_lshlrev_b32_e32 v250, 16, v178
	v_mul_f32_e32 v249, v72, v15
	v_fma_f32 v245, -v17, v249, v250
	v_and_b32_e32 v250, 0xffff0000, v178
	v_mul_f32_e32 v249, v56, v15
	v_fma_f32 v246, -v17, v249, v250
	v_lshlrev_b32_e32 v250, 16, v179
	v_mul_f32_e32 v249, v40, v15
	v_fma_f32 v247, -v17, v249, v250
	v_and_b32_e32 v250, 0xffff0000, v179
	v_mul_f32_e32 v249, v24, v15
	v_fma_f32 v248, -v17, v249, v250
	v_mul_f32_e32 v251, v241, v241
	v_fmac_f32_e32 v251, v240, v240
	v_fmac_f32_e32 v251, v242, v242
	v_fmac_f32_e32 v251, v243, v243
	v_fmac_f32_e32 v251, v245, v245
	v_fmac_f32_e32 v251, v246, v246
	v_fmac_f32_e32 v251, v247, v247
	v_fmac_f32_e32 v251, v248, v248
	s_nop 1
	v_add_f32_dpp v251, v251, v251 quad_perm:[1,0,3,2] row_mask:0xf bank_mask:0xf bound_ctrl:1
	s_nop 1
	v_add_f32_dpp v251, v251, v251 quad_perm:[2,3,0,1] row_mask:0xf bank_mask:0xf bound_ctrl:1
	s_nop 1
	v_add_f32_dpp v251, v251, v251 row_half_mirror row_mask:0xf bank_mask:0xf bound_ctrl:1
	s_nop 1
	v_add_f32_dpp v251, v251, v251 row_mirror row_mask:0xf bank_mask:0xf bound_ctrl:1
	ds_bpermute_b32 v252, v0, v251
	s_waitcnt lgkmcnt(0)
	v_add_f32_e32 v251, v251, v252
	v_fmamk_f32 v251, v251, 0x3b800000, v238
	v_mul_f32_e32 v252, 0x4f800000, v251
	v_cmp_gt_f32_e32 vcc, s24, v251
	s_nop 1
	v_cndmask_b32_e32 v251, v251, v252, vcc
	v_sqrt_f32_e32 v252, v251
	s_nop 0
	v_add_u32_e32 v249, -1, v252
	v_fma_f32 v250, -v249, v252, v251
	v_cmp_ge_f32_e64 s[6:7], 0, v250
	v_add_u32_e32 v250, 1, v252
	s_nop 0
	v_cndmask_b32_e64 v249, v252, v249, s[6:7]
	v_fma_f32 v252, -v250, v252, v251
	v_cmp_lt_f32_e64 s[6:7], 0, v252
	s_nop 1
	v_cndmask_b32_e64 v252, v249, v250, s[6:7]
	v_mul_f32_e32 v249, 0x37800000, v252
	v_cndmask_b32_e32 v252, v252, v249, vcc
	v_cmp_class_f32_e32 vcc, v251, v239
	s_nop 1
	v_cndmask_b32_e32 v251, v252, v251, vcc
	v_div_scale_f32 v252, s[2:3], v251, v251, 1.0
	v_rcp_f32_e32 v249, v252
	s_nop 0
	v_fma_f32 v250, -v252, v249, 1.0
	v_fmac_f32_e32 v249, v250, v249
	v_div_scale_f32 v250, vcc, 1.0, v251, 1.0
	v_mul_f32_e32 v253, v250, v249
	v_fma_f32 v213, -v252, v253, v250
	v_fmac_f32_e32 v253, v213, v249
	v_fma_f32 v252, -v252, v253, v250
	v_div_fmas_f32 v252, v252, v249, v253
	v_div_fixup_f32 v253, v252, v251, 1.0
	v_mul_f32_e32 v240, v240, v253
	v_mul_f32_e32 v241, v241, v253
	v_mul_f32_e32 v242, v242, v253
	v_mul_f32_e32 v243, v243, v253
	v_mul_f32_e32 v245, v245, v253
	v_mul_f32_e32 v246, v246, v253
	v_mul_f32_e32 v247, v247, v253
	v_mul_f32_e32 v248, v248, v253
	v_mul_f32_e32 v240, v224, v240
	v_mul_f32_e32 v241, v225, v241
	v_mul_f32_e32 v242, v226, v242
	v_mul_f32_e32 v243, v227, v243
	v_mul_f32_e32 v245, v228, v245
	v_mul_f32_e32 v246, v229, v246
	v_mul_f32_e32 v247, v230, v247
	v_mul_f32_e32 v248, v231, v248
	v_mov_b32_dpp v232, v240 quad_perm:[1,0,3,2] row_mask:0xf bank_mask:0xf bound_ctrl:1
	v_mov_b32_dpp v233, v241 quad_perm:[1,0,3,2] row_mask:0xf bank_mask:0xf bound_ctrl:1
	v_mov_b32_dpp v234, v242 quad_perm:[1,0,3,2] row_mask:0xf bank_mask:0xf bound_ctrl:1
	v_mov_b32_dpp v235, v243 quad_perm:[1,0,3,2] row_mask:0xf bank_mask:0xf bound_ctrl:1
	v_mov_b32_dpp v2, v245 quad_perm:[1,0,3,2] row_mask:0xf bank_mask:0xf bound_ctrl:1
	v_mov_b32_dpp v3, v246 quad_perm:[1,0,3,2] row_mask:0xf bank_mask:0xf bound_ctrl:1
	v_mov_b32_dpp v5, v247 quad_perm:[1,0,3,2] row_mask:0xf bank_mask:0xf bound_ctrl:1
	v_mov_b32_dpp v151, v248 quad_perm:[1,0,3,2] row_mask:0xf bank_mask:0xf bound_ctrl:1
	v_cvt_pk_bf16_f32 v232, v240, v232
	v_cvt_pk_bf16_f32 v233, v233, v241
	v_cndmask_b32_e64 v232, v233, v232, s[60:61]
	ds_write_b32 v208, v232 offset:1024
	v_cvt_pk_bf16_f32 v234, v242, v234
	v_cvt_pk_bf16_f32 v235, v235, v243
	v_cndmask_b32_e64 v234, v235, v234, s[60:61]
	ds_write_b32 v208, v234 offset:1152
	v_cvt_pk_bf16_f32 v2, v245, v2
	v_cvt_pk_bf16_f32 v3, v3, v246
	v_cndmask_b32_e64 v2, v3, v2, s[60:61]
	ds_write_b32 v208, v2 offset:1280
	v_cvt_pk_bf16_f32 v5, v247, v5
	v_cvt_pk_bf16_f32 v151, v151, v248
	v_cndmask_b32_e64 v5, v151, v5, s[60:61]
	ds_write_b32 v208, v5 offset:1408
	s_waitcnt vmcnt(12)
	v_lshlrev_b32_e32 v250, 16, v180
	v_mul_f32_e32 v249, v137, v14
	v_fma_f32 v240, -v17, v249, v250
	v_and_b32_e32 v250, 0xffff0000, v180
	v_mul_f32_e32 v249, v121, v14
	v_fma_f32 v241, -v17, v249, v250
	v_lshlrev_b32_e32 v250, 16, v181
	v_mul_f32_e32 v249, v105, v14
	v_fma_f32 v242, -v17, v249, v250
	v_and_b32_e32 v250, 0xffff0000, v181
	v_mul_f32_e32 v249, v89, v14
	v_fma_f32 v243, -v17, v249, v250
	v_lshlrev_b32_e32 v250, 16, v182
	v_mul_f32_e32 v249, v73, v14
	v_fma_f32 v245, -v17, v249, v250
	v_and_b32_e32 v250, 0xffff0000, v182
	v_mul_f32_e32 v249, v57, v14
	v_fma_f32 v246, -v17, v249, v250
	v_lshlrev_b32_e32 v250, 16, v183
	v_mul_f32_e32 v249, v41, v14
	v_fma_f32 v247, -v17, v249, v250
	v_and_b32_e32 v250, 0xffff0000, v183
	v_mul_f32_e32 v249, v25, v14
	v_fma_f32 v248, -v17, v249, v250
	v_mul_f32_e32 v251, v241, v241
	v_fmac_f32_e32 v251, v240, v240
	v_fmac_f32_e32 v251, v242, v242
	v_fmac_f32_e32 v251, v243, v243
	v_fmac_f32_e32 v251, v245, v245
	v_fmac_f32_e32 v251, v246, v246
	v_fmac_f32_e32 v251, v247, v247
	v_fmac_f32_e32 v251, v248, v248
	s_nop 1
	v_add_f32_dpp v251, v251, v251 quad_perm:[1,0,3,2] row_mask:0xf bank_mask:0xf bound_ctrl:1
	s_nop 1
	v_add_f32_dpp v251, v251, v251 quad_perm:[2,3,0,1] row_mask:0xf bank_mask:0xf bound_ctrl:1
	s_nop 1
	v_add_f32_dpp v251, v251, v251 row_half_mirror row_mask:0xf bank_mask:0xf bound_ctrl:1
	s_nop 1
	v_add_f32_dpp v251, v251, v251 row_mirror row_mask:0xf bank_mask:0xf bound_ctrl:1
	ds_bpermute_b32 v252, v0, v251
	s_waitcnt lgkmcnt(0)
	v_add_f32_e32 v251, v251, v252
	v_fmamk_f32 v251, v251, 0x3b800000, v238
	v_mul_f32_e32 v252, 0x4f800000, v251
	v_cmp_gt_f32_e32 vcc, s24, v251
	s_nop 1
	v_cndmask_b32_e32 v251, v251, v252, vcc
	v_sqrt_f32_e32 v252, v251
	s_nop 0
	v_add_u32_e32 v249, -1, v252
	v_fma_f32 v250, -v249, v252, v251
	v_cmp_ge_f32_e64 s[6:7], 0, v250
	v_add_u32_e32 v250, 1, v252
	s_nop 0
	v_cndmask_b32_e64 v249, v252, v249, s[6:7]
	v_fma_f32 v252, -v250, v252, v251
	v_cmp_lt_f32_e64 s[6:7], 0, v252
	s_nop 1
	v_cndmask_b32_e64 v252, v249, v250, s[6:7]
	v_mul_f32_e32 v249, 0x37800000, v252
	v_cndmask_b32_e32 v252, v252, v249, vcc
	v_cmp_class_f32_e32 vcc, v251, v239
	s_nop 1
	v_cndmask_b32_e32 v251, v252, v251, vcc
	v_div_scale_f32 v252, s[2:3], v251, v251, 1.0
	v_rcp_f32_e32 v249, v252
	s_nop 0
	v_fma_f32 v250, -v252, v249, 1.0
	v_fmac_f32_e32 v249, v250, v249
	v_div_scale_f32 v250, vcc, 1.0, v251, 1.0
	v_mul_f32_e32 v253, v250, v249
	v_fma_f32 v213, -v252, v253, v250
	v_fmac_f32_e32 v253, v213, v249
	v_fma_f32 v252, -v252, v253, v250
	v_div_fmas_f32 v252, v252, v249, v253
	v_div_fixup_f32 v253, v252, v251, 1.0
	v_mul_f32_e32 v240, v240, v253
	v_mul_f32_e32 v241, v241, v253
	v_mul_f32_e32 v242, v242, v253
	v_mul_f32_e32 v243, v243, v253
	v_mul_f32_e32 v245, v245, v253
	v_mul_f32_e32 v246, v246, v253
	v_mul_f32_e32 v247, v247, v253
	v_mul_f32_e32 v248, v248, v253
	v_mul_f32_e32 v240, v224, v240
	v_mul_f32_e32 v241, v225, v241
	v_mul_f32_e32 v242, v226, v242
	v_mul_f32_e32 v243, v227, v243
	v_mul_f32_e32 v245, v228, v245
	v_mul_f32_e32 v246, v229, v246
	v_mul_f32_e32 v247, v230, v247
	v_mul_f32_e32 v248, v231, v248
	v_mov_b32_dpp v232, v240 quad_perm:[1,0,3,2] row_mask:0xf bank_mask:0xf bound_ctrl:1
	v_mov_b32_dpp v233, v241 quad_perm:[1,0,3,2] row_mask:0xf bank_mask:0xf bound_ctrl:1
	v_mov_b32_dpp v234, v242 quad_perm:[1,0,3,2] row_mask:0xf bank_mask:0xf bound_ctrl:1
	v_mov_b32_dpp v235, v243 quad_perm:[1,0,3,2] row_mask:0xf bank_mask:0xf bound_ctrl:1
	v_mov_b32_dpp v2, v245 quad_perm:[1,0,3,2] row_mask:0xf bank_mask:0xf bound_ctrl:1
	v_mov_b32_dpp v3, v246 quad_perm:[1,0,3,2] row_mask:0xf bank_mask:0xf bound_ctrl:1
	v_mov_b32_dpp v5, v247 quad_perm:[1,0,3,2] row_mask:0xf bank_mask:0xf bound_ctrl:1
	v_mov_b32_dpp v151, v248 quad_perm:[1,0,3,2] row_mask:0xf bank_mask:0xf bound_ctrl:1
	v_cvt_pk_bf16_f32 v232, v240, v232
	v_cvt_pk_bf16_f32 v233, v233, v241
	v_cndmask_b32_e64 v232, v233, v232, s[60:61]
	ds_write_b32 v208, v232 offset:1536
	v_cvt_pk_bf16_f32 v234, v242, v234
	v_cvt_pk_bf16_f32 v235, v235, v243
	v_cndmask_b32_e64 v234, v235, v234, s[60:61]
	ds_write_b32 v208, v234 offset:1664
	v_cvt_pk_bf16_f32 v2, v245, v2
	v_cvt_pk_bf16_f32 v3, v3, v246
	v_cndmask_b32_e64 v2, v3, v2, s[60:61]
	ds_write_b32 v208, v2 offset:1792
	v_cvt_pk_bf16_f32 v5, v247, v5
	v_cvt_pk_bf16_f32 v151, v151, v248
	v_cndmask_b32_e64 v5, v151, v5, s[60:61]
	ds_write_b32 v208, v5 offset:1920
	ds_read_b128 v[168:171], v209 offset:0
	ds_read_b128 v[172:175], v209 offset:1024
	ds_read_b128 v[176:179], v209 offset:2048
	ds_read_b128 v[180:183], v209 offset:3072
	s_waitcnt lgkmcnt(3)
	v_add_u32_e32 v249, 0x8000, v212
	global_store_dwordx4 v249, v[168:171], s[58:59] sc1
	s_waitcnt lgkmcnt(2)
	v_add_u32_e32 v249, 0xa000, v212
	global_store_dwordx4 v249, v[172:175], s[58:59] sc1
	s_waitcnt lgkmcnt(1)
	v_add_u32_e32 v249, 0xc000, v212
	global_store_dwordx4 v249, v[176:179], s[58:59] sc1
	s_waitcnt lgkmcnt(0)
	v_add_u32_e32 v249, 0xe000, v212
	global_store_dwordx4 v249, v[180:183], s[58:59] sc1
	s_waitcnt vmcnt(15)
	v_lshlrev_b32_e32 v250, 16, v184
	v_mul_f32_e32 v249, v138, v13
	v_fma_f32 v240, -v17, v249, v250
	v_and_b32_e32 v250, 0xffff0000, v184
	v_mul_f32_e32 v249, v122, v13
	v_fma_f32 v241, -v17, v249, v250
	v_lshlrev_b32_e32 v250, 16, v185
	v_mul_f32_e32 v249, v106, v13
	v_fma_f32 v242, -v17, v249, v250
	v_and_b32_e32 v250, 0xffff0000, v185
	v_mul_f32_e32 v249, v90, v13
	v_fma_f32 v243, -v17, v249, v250
	v_lshlrev_b32_e32 v250, 16, v186
	v_mul_f32_e32 v249, v74, v13
	v_fma_f32 v245, -v17, v249, v250
	v_and_b32_e32 v250, 0xffff0000, v186
	v_mul_f32_e32 v249, v58, v13
	v_fma_f32 v246, -v17, v249, v250
	v_lshlrev_b32_e32 v250, 16, v187
	v_mul_f32_e32 v249, v42, v13
	v_fma_f32 v247, -v17, v249, v250
	v_and_b32_e32 v250, 0xffff0000, v187
	v_mul_f32_e32 v249, v26, v13
	v_fma_f32 v248, -v17, v249, v250
	v_mul_f32_e32 v251, v241, v241
	v_fmac_f32_e32 v251, v240, v240
	v_fmac_f32_e32 v251, v242, v242
	v_fmac_f32_e32 v251, v243, v243
	v_fmac_f32_e32 v251, v245, v245
	v_fmac_f32_e32 v251, v246, v246
	v_fmac_f32_e32 v251, v247, v247
	v_fmac_f32_e32 v251, v248, v248
	s_nop 1
	v_add_f32_dpp v251, v251, v251 quad_perm:[1,0,3,2] row_mask:0xf bank_mask:0xf bound_ctrl:1
	s_nop 1
	v_add_f32_dpp v251, v251, v251 quad_perm:[2,3,0,1] row_mask:0xf bank_mask:0xf bound_ctrl:1
	s_nop 1
	v_add_f32_dpp v251, v251, v251 row_half_mirror row_mask:0xf bank_mask:0xf bound_ctrl:1
	s_nop 1
	v_add_f32_dpp v251, v251, v251 row_mirror row_mask:0xf bank_mask:0xf bound_ctrl:1
	ds_bpermute_b32 v252, v0, v251
	s_waitcnt lgkmcnt(0)
	v_add_f32_e32 v251, v251, v252
	v_fmamk_f32 v251, v251, 0x3b800000, v238
	v_mul_f32_e32 v252, 0x4f800000, v251
	v_cmp_gt_f32_e32 vcc, s24, v251
	s_nop 1
	v_cndmask_b32_e32 v251, v251, v252, vcc
	v_sqrt_f32_e32 v252, v251
	s_nop 0
	v_add_u32_e32 v249, -1, v252
	v_fma_f32 v250, -v249, v252, v251
	v_cmp_ge_f32_e64 s[6:7], 0, v250
	v_add_u32_e32 v250, 1, v252
	s_nop 0
	v_cndmask_b32_e64 v249, v252, v249, s[6:7]
	v_fma_f32 v252, -v250, v252, v251
	v_cmp_lt_f32_e64 s[6:7], 0, v252
	s_nop 1
	v_cndmask_b32_e64 v252, v249, v250, s[6:7]
	v_mul_f32_e32 v249, 0x37800000, v252
	v_cndmask_b32_e32 v252, v252, v249, vcc
	v_cmp_class_f32_e32 vcc, v251, v239
	s_nop 1
	v_cndmask_b32_e32 v251, v252, v251, vcc
	v_div_scale_f32 v252, s[2:3], v251, v251, 1.0
	v_rcp_f32_e32 v249, v252
	s_nop 0
	v_fma_f32 v250, -v252, v249, 1.0
	v_fmac_f32_e32 v249, v250, v249
	v_div_scale_f32 v250, vcc, 1.0, v251, 1.0
	v_mul_f32_e32 v253, v250, v249
	v_fma_f32 v213, -v252, v253, v250
	v_fmac_f32_e32 v253, v213, v249
	v_fma_f32 v252, -v252, v253, v250
	v_div_fmas_f32 v252, v252, v249, v253
	v_div_fixup_f32 v253, v252, v251, 1.0
	v_mul_f32_e32 v240, v240, v253
	v_mul_f32_e32 v241, v241, v253
	v_mul_f32_e32 v242, v242, v253
	v_mul_f32_e32 v243, v243, v253
	v_mul_f32_e32 v245, v245, v253
	v_mul_f32_e32 v246, v246, v253
	v_mul_f32_e32 v247, v247, v253
	v_mul_f32_e32 v248, v248, v253
	v_mul_f32_e32 v240, v224, v240
	v_mul_f32_e32 v241, v225, v241
	v_mul_f32_e32 v242, v226, v242
	v_mul_f32_e32 v243, v227, v243
	v_mul_f32_e32 v245, v228, v245
	v_mul_f32_e32 v246, v229, v246
	v_mul_f32_e32 v247, v230, v247
	v_mul_f32_e32 v248, v231, v248
	v_mov_b32_dpp v232, v240 quad_perm:[1,0,3,2] row_mask:0xf bank_mask:0xf bound_ctrl:1
	v_mov_b32_dpp v233, v241 quad_perm:[1,0,3,2] row_mask:0xf bank_mask:0xf bound_ctrl:1
	v_mov_b32_dpp v234, v242 quad_perm:[1,0,3,2] row_mask:0xf bank_mask:0xf bound_ctrl:1
	v_mov_b32_dpp v235, v243 quad_perm:[1,0,3,2] row_mask:0xf bank_mask:0xf bound_ctrl:1
	v_mov_b32_dpp v2, v245 quad_perm:[1,0,3,2] row_mask:0xf bank_mask:0xf bound_ctrl:1
	v_mov_b32_dpp v3, v246 quad_perm:[1,0,3,2] row_mask:0xf bank_mask:0xf bound_ctrl:1
	v_mov_b32_dpp v5, v247 quad_perm:[1,0,3,2] row_mask:0xf bank_mask:0xf bound_ctrl:1
	v_mov_b32_dpp v151, v248 quad_perm:[1,0,3,2] row_mask:0xf bank_mask:0xf bound_ctrl:1
	v_cvt_pk_bf16_f32 v232, v240, v232
	v_cvt_pk_bf16_f32 v233, v233, v241
	v_cndmask_b32_e64 v232, v233, v232, s[60:61]
	ds_write_b32 v208, v232 offset:0
	v_cvt_pk_bf16_f32 v234, v242, v234
	v_cvt_pk_bf16_f32 v235, v235, v243
	v_cndmask_b32_e64 v234, v235, v234, s[60:61]
	ds_write_b32 v208, v234 offset:128
	v_cvt_pk_bf16_f32 v2, v245, v2
	v_cvt_pk_bf16_f32 v3, v3, v246
	v_cndmask_b32_e64 v2, v3, v2, s[60:61]
	ds_write_b32 v208, v2 offset:256
	v_cvt_pk_bf16_f32 v5, v247, v5
	v_cvt_pk_bf16_f32 v151, v151, v248
	v_cndmask_b32_e64 v5, v151, v5, s[60:61]
	ds_write_b32 v208, v5 offset:384
	s_waitcnt vmcnt(14)
	v_lshlrev_b32_e32 v250, 16, v188
	v_mul_f32_e32 v249, v139, v12
	v_fma_f32 v240, -v17, v249, v250
	v_and_b32_e32 v250, 0xffff0000, v188
	v_mul_f32_e32 v249, v123, v12
	v_fma_f32 v241, -v17, v249, v250
	v_lshlrev_b32_e32 v250, 16, v189
	v_mul_f32_e32 v249, v107, v12
	v_fma_f32 v242, -v17, v249, v250
	v_and_b32_e32 v250, 0xffff0000, v189
	v_mul_f32_e32 v249, v91, v12
	v_fma_f32 v243, -v17, v249, v250
	v_lshlrev_b32_e32 v250, 16, v190
	v_mul_f32_e32 v249, v75, v12
	v_fma_f32 v245, -v17, v249, v250
	v_and_b32_e32 v250, 0xffff0000, v190
	v_mul_f32_e32 v249, v59, v12
	v_fma_f32 v246, -v17, v249, v250
	v_lshlrev_b32_e32 v250, 16, v191
	v_mul_f32_e32 v249, v43, v12
	v_fma_f32 v247, -v17, v249, v250
	v_and_b32_e32 v250, 0xffff0000, v191
	v_mul_f32_e32 v249, v27, v12
	v_fma_f32 v248, -v17, v249, v250
	v_mul_f32_e32 v251, v241, v241
	v_fmac_f32_e32 v251, v240, v240
	v_fmac_f32_e32 v251, v242, v242
	v_fmac_f32_e32 v251, v243, v243
	v_fmac_f32_e32 v251, v245, v245
	v_fmac_f32_e32 v251, v246, v246
	v_fmac_f32_e32 v251, v247, v247
	v_fmac_f32_e32 v251, v248, v248
	s_nop 1
	v_add_f32_dpp v251, v251, v251 quad_perm:[1,0,3,2] row_mask:0xf bank_mask:0xf bound_ctrl:1
	s_nop 1
	v_add_f32_dpp v251, v251, v251 quad_perm:[2,3,0,1] row_mask:0xf bank_mask:0xf bound_ctrl:1
	s_nop 1
	v_add_f32_dpp v251, v251, v251 row_half_mirror row_mask:0xf bank_mask:0xf bound_ctrl:1
	s_nop 1
	v_add_f32_dpp v251, v251, v251 row_mirror row_mask:0xf bank_mask:0xf bound_ctrl:1
	ds_bpermute_b32 v252, v0, v251
	s_waitcnt lgkmcnt(0)
	v_add_f32_e32 v251, v251, v252
	v_fmamk_f32 v251, v251, 0x3b800000, v238
	v_mul_f32_e32 v252, 0x4f800000, v251
	v_cmp_gt_f32_e32 vcc, s24, v251
	s_nop 1
	v_cndmask_b32_e32 v251, v251, v252, vcc
	v_sqrt_f32_e32 v252, v251
	s_nop 0
	v_add_u32_e32 v249, -1, v252
	v_fma_f32 v250, -v249, v252, v251
	v_cmp_ge_f32_e64 s[6:7], 0, v250
	v_add_u32_e32 v250, 1, v252
	s_nop 0
	v_cndmask_b32_e64 v249, v252, v249, s[6:7]
	v_fma_f32 v252, -v250, v252, v251
	v_cmp_lt_f32_e64 s[6:7], 0, v252
	s_nop 1
	v_cndmask_b32_e64 v252, v249, v250, s[6:7]
	v_mul_f32_e32 v249, 0x37800000, v252
	v_cndmask_b32_e32 v252, v252, v249, vcc
	v_cmp_class_f32_e32 vcc, v251, v239
	s_nop 1
	v_cndmask_b32_e32 v251, v252, v251, vcc
	v_div_scale_f32 v252, s[2:3], v251, v251, 1.0
	v_rcp_f32_e32 v249, v252
	s_nop 0
	v_fma_f32 v250, -v252, v249, 1.0
	v_fmac_f32_e32 v249, v250, v249
	v_div_scale_f32 v250, vcc, 1.0, v251, 1.0
	v_mul_f32_e32 v253, v250, v249
	v_fma_f32 v213, -v252, v253, v250
	v_fmac_f32_e32 v253, v213, v249
	v_fma_f32 v252, -v252, v253, v250
	v_div_fmas_f32 v252, v252, v249, v253
	v_div_fixup_f32 v253, v252, v251, 1.0
	v_mul_f32_e32 v240, v240, v253
	v_mul_f32_e32 v241, v241, v253
	v_mul_f32_e32 v242, v242, v253
	v_mul_f32_e32 v243, v243, v253
	v_mul_f32_e32 v245, v245, v253
	v_mul_f32_e32 v246, v246, v253
	v_mul_f32_e32 v247, v247, v253
	v_mul_f32_e32 v248, v248, v253
	v_mul_f32_e32 v240, v224, v240
	v_mul_f32_e32 v241, v225, v241
	v_mul_f32_e32 v242, v226, v242
	v_mul_f32_e32 v243, v227, v243
	v_mul_f32_e32 v245, v228, v245
	v_mul_f32_e32 v246, v229, v246
	v_mul_f32_e32 v247, v230, v247
	v_mul_f32_e32 v248, v231, v248
	v_mov_b32_dpp v232, v240 quad_perm:[1,0,3,2] row_mask:0xf bank_mask:0xf bound_ctrl:1
	v_mov_b32_dpp v233, v241 quad_perm:[1,0,3,2] row_mask:0xf bank_mask:0xf bound_ctrl:1
	v_mov_b32_dpp v234, v242 quad_perm:[1,0,3,2] row_mask:0xf bank_mask:0xf bound_ctrl:1
	v_mov_b32_dpp v235, v243 quad_perm:[1,0,3,2] row_mask:0xf bank_mask:0xf bound_ctrl:1
	v_mov_b32_dpp v2, v245 quad_perm:[1,0,3,2] row_mask:0xf bank_mask:0xf bound_ctrl:1
	v_mov_b32_dpp v3, v246 quad_perm:[1,0,3,2] row_mask:0xf bank_mask:0xf bound_ctrl:1
	v_mov_b32_dpp v5, v247 quad_perm:[1,0,3,2] row_mask:0xf bank_mask:0xf bound_ctrl:1
	v_mov_b32_dpp v151, v248 quad_perm:[1,0,3,2] row_mask:0xf bank_mask:0xf bound_ctrl:1
	v_cvt_pk_bf16_f32 v232, v240, v232
	v_cvt_pk_bf16_f32 v233, v233, v241
	v_cndmask_b32_e64 v232, v233, v232, s[60:61]
	ds_write_b32 v208, v232 offset:512
	v_cvt_pk_bf16_f32 v234, v242, v234
	v_cvt_pk_bf16_f32 v235, v235, v243
	v_cndmask_b32_e64 v234, v235, v234, s[60:61]
	ds_write_b32 v208, v234 offset:640
	v_cvt_pk_bf16_f32 v2, v245, v2
	v_cvt_pk_bf16_f32 v3, v3, v246
	v_cndmask_b32_e64 v2, v3, v2, s[60:61]
	ds_write_b32 v208, v2 offset:768
	v_cvt_pk_bf16_f32 v5, v247, v5
	v_cvt_pk_bf16_f32 v151, v151, v248
	v_cndmask_b32_e64 v5, v151, v5, s[60:61]
	ds_write_b32 v208, v5 offset:896
	s_waitcnt vmcnt(13)
	v_lshlrev_b32_e32 v250, 16, v192
	v_mul_f32_e32 v249, v140, v11
	v_fma_f32 v240, -v17, v249, v250
	v_and_b32_e32 v250, 0xffff0000, v192
	v_mul_f32_e32 v249, v124, v11
	v_fma_f32 v241, -v17, v249, v250
	v_lshlrev_b32_e32 v250, 16, v193
	v_mul_f32_e32 v249, v108, v11
	v_fma_f32 v242, -v17, v249, v250
	v_and_b32_e32 v250, 0xffff0000, v193
	v_mul_f32_e32 v249, v92, v11
	v_fma_f32 v243, -v17, v249, v250
	v_lshlrev_b32_e32 v250, 16, v194
	v_mul_f32_e32 v249, v76, v11
	v_fma_f32 v245, -v17, v249, v250
	v_and_b32_e32 v250, 0xffff0000, v194
	v_mul_f32_e32 v249, v60, v11
	v_fma_f32 v246, -v17, v249, v250
	v_lshlrev_b32_e32 v250, 16, v195
	v_mul_f32_e32 v249, v44, v11
	v_fma_f32 v247, -v17, v249, v250
	v_and_b32_e32 v250, 0xffff0000, v195
	v_mul_f32_e32 v249, v28, v11
	v_fma_f32 v248, -v17, v249, v250
	v_mul_f32_e32 v251, v241, v241
	v_fmac_f32_e32 v251, v240, v240
	v_fmac_f32_e32 v251, v242, v242
	v_fmac_f32_e32 v251, v243, v243
	v_fmac_f32_e32 v251, v245, v245
	v_fmac_f32_e32 v251, v246, v246
	v_fmac_f32_e32 v251, v247, v247
	v_fmac_f32_e32 v251, v248, v248
	s_nop 1
	v_add_f32_dpp v251, v251, v251 quad_perm:[1,0,3,2] row_mask:0xf bank_mask:0xf bound_ctrl:1
	s_nop 1
	v_add_f32_dpp v251, v251, v251 quad_perm:[2,3,0,1] row_mask:0xf bank_mask:0xf bound_ctrl:1
	s_nop 1
	v_add_f32_dpp v251, v251, v251 row_half_mirror row_mask:0xf bank_mask:0xf bound_ctrl:1
	s_nop 1
	v_add_f32_dpp v251, v251, v251 row_mirror row_mask:0xf bank_mask:0xf bound_ctrl:1
	ds_bpermute_b32 v252, v0, v251
	s_waitcnt lgkmcnt(0)
	v_add_f32_e32 v251, v251, v252
	v_fmamk_f32 v251, v251, 0x3b800000, v238
	v_mul_f32_e32 v252, 0x4f800000, v251
	v_cmp_gt_f32_e32 vcc, s24, v251
	s_nop 1
	v_cndmask_b32_e32 v251, v251, v252, vcc
	v_sqrt_f32_e32 v252, v251
	s_nop 0
	v_add_u32_e32 v249, -1, v252
	v_fma_f32 v250, -v249, v252, v251
	v_cmp_ge_f32_e64 s[6:7], 0, v250
	v_add_u32_e32 v250, 1, v252
	s_nop 0
	v_cndmask_b32_e64 v249, v252, v249, s[6:7]
	v_fma_f32 v252, -v250, v252, v251
	v_cmp_lt_f32_e64 s[6:7], 0, v252
	s_nop 1
	v_cndmask_b32_e64 v252, v249, v250, s[6:7]
	v_mul_f32_e32 v249, 0x37800000, v252
	v_cndmask_b32_e32 v252, v252, v249, vcc
	v_cmp_class_f32_e32 vcc, v251, v239
	s_nop 1
	v_cndmask_b32_e32 v251, v252, v251, vcc
	v_div_scale_f32 v252, s[2:3], v251, v251, 1.0
	v_rcp_f32_e32 v249, v252
	s_nop 0
	v_fma_f32 v250, -v252, v249, 1.0
	v_fmac_f32_e32 v249, v250, v249
	v_div_scale_f32 v250, vcc, 1.0, v251, 1.0
	v_mul_f32_e32 v253, v250, v249
	v_fma_f32 v213, -v252, v253, v250
	v_fmac_f32_e32 v253, v213, v249
	v_fma_f32 v252, -v252, v253, v250
	v_div_fmas_f32 v252, v252, v249, v253
	v_div_fixup_f32 v253, v252, v251, 1.0
	v_mul_f32_e32 v240, v240, v253
	v_mul_f32_e32 v241, v241, v253
	v_mul_f32_e32 v242, v242, v253
	v_mul_f32_e32 v243, v243, v253
	v_mul_f32_e32 v245, v245, v253
	v_mul_f32_e32 v246, v246, v253
	v_mul_f32_e32 v247, v247, v253
	v_mul_f32_e32 v248, v248, v253
	v_mul_f32_e32 v240, v224, v240
	v_mul_f32_e32 v241, v225, v241
	v_mul_f32_e32 v242, v226, v242
	v_mul_f32_e32 v243, v227, v243
	v_mul_f32_e32 v245, v228, v245
	v_mul_f32_e32 v246, v229, v246
	v_mul_f32_e32 v247, v230, v247
	v_mul_f32_e32 v248, v231, v248
	v_mov_b32_dpp v232, v240 quad_perm:[1,0,3,2] row_mask:0xf bank_mask:0xf bound_ctrl:1
	v_mov_b32_dpp v233, v241 quad_perm:[1,0,3,2] row_mask:0xf bank_mask:0xf bound_ctrl:1
	v_mov_b32_dpp v234, v242 quad_perm:[1,0,3,2] row_mask:0xf bank_mask:0xf bound_ctrl:1
	v_mov_b32_dpp v235, v243 quad_perm:[1,0,3,2] row_mask:0xf bank_mask:0xf bound_ctrl:1
	v_mov_b32_dpp v2, v245 quad_perm:[1,0,3,2] row_mask:0xf bank_mask:0xf bound_ctrl:1
	v_mov_b32_dpp v3, v246 quad_perm:[1,0,3,2] row_mask:0xf bank_mask:0xf bound_ctrl:1
	v_mov_b32_dpp v5, v247 quad_perm:[1,0,3,2] row_mask:0xf bank_mask:0xf bound_ctrl:1
	v_mov_b32_dpp v151, v248 quad_perm:[1,0,3,2] row_mask:0xf bank_mask:0xf bound_ctrl:1
	v_cvt_pk_bf16_f32 v232, v240, v232
	v_cvt_pk_bf16_f32 v233, v233, v241
	v_cndmask_b32_e64 v232, v233, v232, s[60:61]
	ds_write_b32 v208, v232 offset:1024
	v_cvt_pk_bf16_f32 v234, v242, v234
	v_cvt_pk_bf16_f32 v235, v235, v243
	v_cndmask_b32_e64 v234, v235, v234, s[60:61]
	ds_write_b32 v208, v234 offset:1152
	v_cvt_pk_bf16_f32 v2, v245, v2
	v_cvt_pk_bf16_f32 v3, v3, v246
	v_cndmask_b32_e64 v2, v3, v2, s[60:61]
	ds_write_b32 v208, v2 offset:1280
	v_cvt_pk_bf16_f32 v5, v247, v5
	v_cvt_pk_bf16_f32 v151, v151, v248
	v_cndmask_b32_e64 v5, v151, v5, s[60:61]
	ds_write_b32 v208, v5 offset:1408
	s_waitcnt vmcnt(12)
	v_lshlrev_b32_e32 v250, 16, v196
	v_mul_f32_e32 v249, v141, v10
	v_fma_f32 v240, -v17, v249, v250
	v_and_b32_e32 v250, 0xffff0000, v196
	v_mul_f32_e32 v249, v125, v10
	v_fma_f32 v241, -v17, v249, v250
	v_lshlrev_b32_e32 v250, 16, v197
	v_mul_f32_e32 v249, v109, v10
	v_fma_f32 v242, -v17, v249, v250
	v_and_b32_e32 v250, 0xffff0000, v197
	v_mul_f32_e32 v249, v93, v10
	v_fma_f32 v243, -v17, v249, v250
	v_lshlrev_b32_e32 v250, 16, v198
	v_mul_f32_e32 v249, v77, v10
	v_fma_f32 v245, -v17, v249, v250
	v_and_b32_e32 v250, 0xffff0000, v198
	v_mul_f32_e32 v249, v61, v10
	v_fma_f32 v246, -v17, v249, v250
	v_lshlrev_b32_e32 v250, 16, v199
	v_mul_f32_e32 v249, v45, v10
	v_fma_f32 v247, -v17, v249, v250
	v_and_b32_e32 v250, 0xffff0000, v199
	v_mul_f32_e32 v249, v29, v10
	v_fma_f32 v248, -v17, v249, v250
	v_mul_f32_e32 v251, v241, v241
	v_fmac_f32_e32 v251, v240, v240
	v_fmac_f32_e32 v251, v242, v242
	v_fmac_f32_e32 v251, v243, v243
	v_fmac_f32_e32 v251, v245, v245
	v_fmac_f32_e32 v251, v246, v246
	v_fmac_f32_e32 v251, v247, v247
	v_fmac_f32_e32 v251, v248, v248
	s_nop 1
	v_add_f32_dpp v251, v251, v251 quad_perm:[1,0,3,2] row_mask:0xf bank_mask:0xf bound_ctrl:1
	s_nop 1
	v_add_f32_dpp v251, v251, v251 quad_perm:[2,3,0,1] row_mask:0xf bank_mask:0xf bound_ctrl:1
	s_nop 1
	v_add_f32_dpp v251, v251, v251 row_half_mirror row_mask:0xf bank_mask:0xf bound_ctrl:1
	s_nop 1
	v_add_f32_dpp v251, v251, v251 row_mirror row_mask:0xf bank_mask:0xf bound_ctrl:1
	ds_bpermute_b32 v252, v0, v251
	s_waitcnt lgkmcnt(0)
	v_add_f32_e32 v251, v251, v252
	v_fmamk_f32 v251, v251, 0x3b800000, v238
	v_mul_f32_e32 v252, 0x4f800000, v251
	v_cmp_gt_f32_e32 vcc, s24, v251
	s_nop 1
	v_cndmask_b32_e32 v251, v251, v252, vcc
	v_sqrt_f32_e32 v252, v251
	s_nop 0
	v_add_u32_e32 v249, -1, v252
	v_fma_f32 v250, -v249, v252, v251
	v_cmp_ge_f32_e64 s[6:7], 0, v250
	v_add_u32_e32 v250, 1, v252
	s_nop 0
	v_cndmask_b32_e64 v249, v252, v249, s[6:7]
	v_fma_f32 v252, -v250, v252, v251
	v_cmp_lt_f32_e64 s[6:7], 0, v252
	s_nop 1
	v_cndmask_b32_e64 v252, v249, v250, s[6:7]
	v_mul_f32_e32 v249, 0x37800000, v252
	v_cndmask_b32_e32 v252, v252, v249, vcc
	v_cmp_class_f32_e32 vcc, v251, v239
	s_nop 1
	v_cndmask_b32_e32 v251, v252, v251, vcc
	v_div_scale_f32 v252, s[2:3], v251, v251, 1.0
	v_rcp_f32_e32 v249, v252
	s_nop 0
	v_fma_f32 v250, -v252, v249, 1.0
	v_fmac_f32_e32 v249, v250, v249
	v_div_scale_f32 v250, vcc, 1.0, v251, 1.0
	v_mul_f32_e32 v253, v250, v249
	v_fma_f32 v213, -v252, v253, v250
	v_fmac_f32_e32 v253, v213, v249
	v_fma_f32 v252, -v252, v253, v250
	v_div_fmas_f32 v252, v252, v249, v253
	v_div_fixup_f32 v253, v252, v251, 1.0
	v_mul_f32_e32 v240, v240, v253
	v_mul_f32_e32 v241, v241, v253
	v_mul_f32_e32 v242, v242, v253
	v_mul_f32_e32 v243, v243, v253
	v_mul_f32_e32 v245, v245, v253
	v_mul_f32_e32 v246, v246, v253
	v_mul_f32_e32 v247, v247, v253
	v_mul_f32_e32 v248, v248, v253
	v_mul_f32_e32 v240, v224, v240
	v_mul_f32_e32 v241, v225, v241
	v_mul_f32_e32 v242, v226, v242
	v_mul_f32_e32 v243, v227, v243
	v_mul_f32_e32 v245, v228, v245
	v_mul_f32_e32 v246, v229, v246
	v_mul_f32_e32 v247, v230, v247
	v_mul_f32_e32 v248, v231, v248
	v_mov_b32_dpp v232, v240 quad_perm:[1,0,3,2] row_mask:0xf bank_mask:0xf bound_ctrl:1
	v_mov_b32_dpp v233, v241 quad_perm:[1,0,3,2] row_mask:0xf bank_mask:0xf bound_ctrl:1
	v_mov_b32_dpp v234, v242 quad_perm:[1,0,3,2] row_mask:0xf bank_mask:0xf bound_ctrl:1
	v_mov_b32_dpp v235, v243 quad_perm:[1,0,3,2] row_mask:0xf bank_mask:0xf bound_ctrl:1
	v_mov_b32_dpp v2, v245 quad_perm:[1,0,3,2] row_mask:0xf bank_mask:0xf bound_ctrl:1
	v_mov_b32_dpp v3, v246 quad_perm:[1,0,3,2] row_mask:0xf bank_mask:0xf bound_ctrl:1
	v_mov_b32_dpp v5, v247 quad_perm:[1,0,3,2] row_mask:0xf bank_mask:0xf bound_ctrl:1
	v_mov_b32_dpp v151, v248 quad_perm:[1,0,3,2] row_mask:0xf bank_mask:0xf bound_ctrl:1
	v_cvt_pk_bf16_f32 v232, v240, v232
	v_cvt_pk_bf16_f32 v233, v233, v241
	v_cndmask_b32_e64 v232, v233, v232, s[60:61]
	ds_write_b32 v208, v232 offset:1536
	v_cvt_pk_bf16_f32 v234, v242, v234
	v_cvt_pk_bf16_f32 v235, v235, v243
	v_cndmask_b32_e64 v234, v235, v234, s[60:61]
	ds_write_b32 v208, v234 offset:1664
	v_cvt_pk_bf16_f32 v2, v245, v2
	v_cvt_pk_bf16_f32 v3, v3, v246
	v_cndmask_b32_e64 v2, v3, v2, s[60:61]
	ds_write_b32 v208, v2 offset:1792
	v_cvt_pk_bf16_f32 v5, v247, v5
	v_cvt_pk_bf16_f32 v151, v151, v248
	v_cndmask_b32_e64 v5, v151, v5, s[60:61]
	ds_write_b32 v208, v5 offset:1920
	ds_read_b128 v[184:187], v209 offset:0
	ds_read_b128 v[188:191], v209 offset:1024
	ds_read_b128 v[192:195], v209 offset:2048
	ds_read_b128 v[196:199], v209 offset:3072
	s_waitcnt lgkmcnt(3)
	v_add_u32_e32 v249, 0x10000, v212
	global_store_dwordx4 v249, v[184:187], s[58:59] sc1
	s_waitcnt lgkmcnt(2)
	v_add_u32_e32 v249, 0x12000, v212
	global_store_dwordx4 v249, v[188:191], s[58:59] sc1
	s_waitcnt lgkmcnt(1)
	v_add_u32_e32 v249, 0x14000, v212
	global_store_dwordx4 v249, v[192:195], s[58:59] sc1
	s_waitcnt lgkmcnt(0)
	v_add_u32_e32 v249, 0x16000, v212
	global_store_dwordx4 v249, v[196:199], s[58:59] sc1
	s_waitcnt vmcnt(15)
	v_lshlrev_b32_e32 v250, 16, v200
	v_mul_f32_e32 v249, v142, v9
	v_fma_f32 v240, -v17, v249, v250
	v_and_b32_e32 v250, 0xffff0000, v200
	v_mul_f32_e32 v249, v126, v9
	v_fma_f32 v241, -v17, v249, v250
	v_lshlrev_b32_e32 v250, 16, v201
	v_mul_f32_e32 v249, v110, v9
	v_fma_f32 v242, -v17, v249, v250
	v_and_b32_e32 v250, 0xffff0000, v201
	v_mul_f32_e32 v249, v94, v9
	v_fma_f32 v243, -v17, v249, v250
	v_lshlrev_b32_e32 v250, 16, v202
	v_mul_f32_e32 v249, v78, v9
	v_fma_f32 v245, -v17, v249, v250
	v_and_b32_e32 v250, 0xffff0000, v202
	v_mul_f32_e32 v249, v62, v9
	v_fma_f32 v246, -v17, v249, v250
	v_lshlrev_b32_e32 v250, 16, v203
	v_mul_f32_e32 v249, v46, v9
	v_fma_f32 v247, -v17, v249, v250
	v_and_b32_e32 v250, 0xffff0000, v203
	v_mul_f32_e32 v249, v30, v9
	v_fma_f32 v248, -v17, v249, v250
	v_mul_f32_e32 v251, v241, v241
	v_fmac_f32_e32 v251, v240, v240
	v_fmac_f32_e32 v251, v242, v242
	v_fmac_f32_e32 v251, v243, v243
	v_fmac_f32_e32 v251, v245, v245
	v_fmac_f32_e32 v251, v246, v246
	v_fmac_f32_e32 v251, v247, v247
	v_fmac_f32_e32 v251, v248, v248
	s_nop 1
	v_add_f32_dpp v251, v251, v251 quad_perm:[1,0,3,2] row_mask:0xf bank_mask:0xf bound_ctrl:1
	s_nop 1
	v_add_f32_dpp v251, v251, v251 quad_perm:[2,3,0,1] row_mask:0xf bank_mask:0xf bound_ctrl:1
	s_nop 1
	v_add_f32_dpp v251, v251, v251 row_half_mirror row_mask:0xf bank_mask:0xf bound_ctrl:1
	s_nop 1
	v_add_f32_dpp v251, v251, v251 row_mirror row_mask:0xf bank_mask:0xf bound_ctrl:1
	ds_bpermute_b32 v252, v0, v251
	s_waitcnt lgkmcnt(0)
	v_add_f32_e32 v251, v251, v252
	v_fmamk_f32 v251, v251, 0x3b800000, v238
	v_mul_f32_e32 v252, 0x4f800000, v251
	v_cmp_gt_f32_e32 vcc, s24, v251
	s_nop 1
	v_cndmask_b32_e32 v251, v251, v252, vcc
	v_sqrt_f32_e32 v252, v251
	s_nop 0
	v_add_u32_e32 v249, -1, v252
	v_fma_f32 v250, -v249, v252, v251
	v_cmp_ge_f32_e64 s[6:7], 0, v250
	v_add_u32_e32 v250, 1, v252
	s_nop 0
	v_cndmask_b32_e64 v249, v252, v249, s[6:7]
	v_fma_f32 v252, -v250, v252, v251
	v_cmp_lt_f32_e64 s[6:7], 0, v252
	s_nop 1
	v_cndmask_b32_e64 v252, v249, v250, s[6:7]
	v_mul_f32_e32 v249, 0x37800000, v252
	v_cndmask_b32_e32 v252, v252, v249, vcc
	v_cmp_class_f32_e32 vcc, v251, v239
	s_nop 1
	v_cndmask_b32_e32 v251, v252, v251, vcc
	v_div_scale_f32 v252, s[2:3], v251, v251, 1.0
	v_rcp_f32_e32 v249, v252
	s_nop 0
	v_fma_f32 v250, -v252, v249, 1.0
	v_fmac_f32_e32 v249, v250, v249
	v_div_scale_f32 v250, vcc, 1.0, v251, 1.0
	v_mul_f32_e32 v253, v250, v249
	v_fma_f32 v213, -v252, v253, v250
	v_fmac_f32_e32 v253, v213, v249
	v_fma_f32 v252, -v252, v253, v250
	v_div_fmas_f32 v252, v252, v249, v253
	v_div_fixup_f32 v253, v252, v251, 1.0
	v_mul_f32_e32 v240, v240, v253
	v_mul_f32_e32 v241, v241, v253
	v_mul_f32_e32 v242, v242, v253
	v_mul_f32_e32 v243, v243, v253
	v_mul_f32_e32 v245, v245, v253
	v_mul_f32_e32 v246, v246, v253
	v_mul_f32_e32 v247, v247, v253
	v_mul_f32_e32 v248, v248, v253
	v_mul_f32_e32 v240, v224, v240
	v_mul_f32_e32 v241, v225, v241
	v_mul_f32_e32 v242, v226, v242
	v_mul_f32_e32 v243, v227, v243
	v_mul_f32_e32 v245, v228, v245
	v_mul_f32_e32 v246, v229, v246
	v_mul_f32_e32 v247, v230, v247
	v_mul_f32_e32 v248, v231, v248
	v_mov_b32_dpp v232, v240 quad_perm:[1,0,3,2] row_mask:0xf bank_mask:0xf bound_ctrl:1
	v_mov_b32_dpp v233, v241 quad_perm:[1,0,3,2] row_mask:0xf bank_mask:0xf bound_ctrl:1
	v_mov_b32_dpp v234, v242 quad_perm:[1,0,3,2] row_mask:0xf bank_mask:0xf bound_ctrl:1
	v_mov_b32_dpp v235, v243 quad_perm:[1,0,3,2] row_mask:0xf bank_mask:0xf bound_ctrl:1
	v_mov_b32_dpp v2, v245 quad_perm:[1,0,3,2] row_mask:0xf bank_mask:0xf bound_ctrl:1
	v_mov_b32_dpp v3, v246 quad_perm:[1,0,3,2] row_mask:0xf bank_mask:0xf bound_ctrl:1
	v_mov_b32_dpp v5, v247 quad_perm:[1,0,3,2] row_mask:0xf bank_mask:0xf bound_ctrl:1
	v_mov_b32_dpp v151, v248 quad_perm:[1,0,3,2] row_mask:0xf bank_mask:0xf bound_ctrl:1
	v_cvt_pk_bf16_f32 v232, v240, v232
	v_cvt_pk_bf16_f32 v233, v233, v241
	v_cndmask_b32_e64 v232, v233, v232, s[60:61]
	ds_write_b32 v208, v232 offset:0
	v_cvt_pk_bf16_f32 v234, v242, v234
	v_cvt_pk_bf16_f32 v235, v235, v243
	v_cndmask_b32_e64 v234, v235, v234, s[60:61]
	ds_write_b32 v208, v234 offset:128
	v_cvt_pk_bf16_f32 v2, v245, v2
	v_cvt_pk_bf16_f32 v3, v3, v246
	v_cndmask_b32_e64 v2, v3, v2, s[60:61]
	ds_write_b32 v208, v2 offset:256
	v_cvt_pk_bf16_f32 v5, v247, v5
	v_cvt_pk_bf16_f32 v151, v151, v248
	v_cndmask_b32_e64 v5, v151, v5, s[60:61]
	ds_write_b32 v208, v5 offset:384
	s_waitcnt vmcnt(14)
	v_lshlrev_b32_e32 v250, 16, v204
	v_mul_f32_e32 v249, v143, v8
	v_fma_f32 v240, -v17, v249, v250
	v_and_b32_e32 v250, 0xffff0000, v204
	v_mul_f32_e32 v249, v127, v8
	v_fma_f32 v241, -v17, v249, v250
	v_lshlrev_b32_e32 v250, 16, v205
	v_mul_f32_e32 v249, v111, v8
	v_fma_f32 v242, -v17, v249, v250
	v_and_b32_e32 v250, 0xffff0000, v205
	v_mul_f32_e32 v249, v95, v8
	v_fma_f32 v243, -v17, v249, v250
	v_lshlrev_b32_e32 v250, 16, v206
	v_mul_f32_e32 v249, v79, v8
	v_fma_f32 v245, -v17, v249, v250
	v_and_b32_e32 v250, 0xffff0000, v206
	v_mul_f32_e32 v249, v63, v8
	v_fma_f32 v246, -v17, v249, v250
	v_lshlrev_b32_e32 v250, 16, v207
	v_mul_f32_e32 v249, v47, v8
	v_fma_f32 v247, -v17, v249, v250
	v_and_b32_e32 v250, 0xffff0000, v207
	v_mul_f32_e32 v249, v31, v8
	v_fma_f32 v248, -v17, v249, v250
	v_mul_f32_e32 v251, v241, v241
	v_fmac_f32_e32 v251, v240, v240
	v_fmac_f32_e32 v251, v242, v242
	v_fmac_f32_e32 v251, v243, v243
	v_fmac_f32_e32 v251, v245, v245
	v_fmac_f32_e32 v251, v246, v246
	v_fmac_f32_e32 v251, v247, v247
	v_fmac_f32_e32 v251, v248, v248
	s_nop 1
	v_add_f32_dpp v251, v251, v251 quad_perm:[1,0,3,2] row_mask:0xf bank_mask:0xf bound_ctrl:1
	s_nop 1
	v_add_f32_dpp v251, v251, v251 quad_perm:[2,3,0,1] row_mask:0xf bank_mask:0xf bound_ctrl:1
	s_nop 1
	v_add_f32_dpp v251, v251, v251 row_half_mirror row_mask:0xf bank_mask:0xf bound_ctrl:1
	s_nop 1
	v_add_f32_dpp v251, v251, v251 row_mirror row_mask:0xf bank_mask:0xf bound_ctrl:1
	ds_bpermute_b32 v252, v0, v251
	s_waitcnt lgkmcnt(0)
	v_add_f32_e32 v251, v251, v252
	v_fmamk_f32 v251, v251, 0x3b800000, v238
	v_mul_f32_e32 v252, 0x4f800000, v251
	v_cmp_gt_f32_e32 vcc, s24, v251
	s_nop 1
	v_cndmask_b32_e32 v251, v251, v252, vcc
	v_sqrt_f32_e32 v252, v251
	s_nop 0
	v_add_u32_e32 v249, -1, v252
	v_fma_f32 v250, -v249, v252, v251
	v_cmp_ge_f32_e64 s[6:7], 0, v250
	v_add_u32_e32 v250, 1, v252
	s_nop 0
	v_cndmask_b32_e64 v249, v252, v249, s[6:7]
	v_fma_f32 v252, -v250, v252, v251
	v_cmp_lt_f32_e64 s[6:7], 0, v252
	s_nop 1
	v_cndmask_b32_e64 v252, v249, v250, s[6:7]
	v_mul_f32_e32 v249, 0x37800000, v252
	v_cndmask_b32_e32 v252, v252, v249, vcc
	v_cmp_class_f32_e32 vcc, v251, v239
	s_nop 1
	v_cndmask_b32_e32 v251, v252, v251, vcc
	v_div_scale_f32 v252, s[2:3], v251, v251, 1.0
	v_rcp_f32_e32 v249, v252
	s_nop 0
	v_fma_f32 v250, -v252, v249, 1.0
	v_fmac_f32_e32 v249, v250, v249
	v_div_scale_f32 v250, vcc, 1.0, v251, 1.0
	v_mul_f32_e32 v253, v250, v249
	v_fma_f32 v213, -v252, v253, v250
	v_fmac_f32_e32 v253, v213, v249
	v_fma_f32 v252, -v252, v253, v250
	v_div_fmas_f32 v252, v252, v249, v253
	v_div_fixup_f32 v253, v252, v251, 1.0
	v_mul_f32_e32 v240, v240, v253
	v_mul_f32_e32 v241, v241, v253
	v_mul_f32_e32 v242, v242, v253
	v_mul_f32_e32 v243, v243, v253
	v_mul_f32_e32 v245, v245, v253
	v_mul_f32_e32 v246, v246, v253
	v_mul_f32_e32 v247, v247, v253
	v_mul_f32_e32 v248, v248, v253
	v_mul_f32_e32 v240, v224, v240
	v_mul_f32_e32 v241, v225, v241
	v_mul_f32_e32 v242, v226, v242
	v_mul_f32_e32 v243, v227, v243
	v_mul_f32_e32 v245, v228, v245
	v_mul_f32_e32 v246, v229, v246
	v_mul_f32_e32 v247, v230, v247
	v_mul_f32_e32 v248, v231, v248
	v_mov_b32_dpp v232, v240 quad_perm:[1,0,3,2] row_mask:0xf bank_mask:0xf bound_ctrl:1
	v_mov_b32_dpp v233, v241 quad_perm:[1,0,3,2] row_mask:0xf bank_mask:0xf bound_ctrl:1
	v_mov_b32_dpp v234, v242 quad_perm:[1,0,3,2] row_mask:0xf bank_mask:0xf bound_ctrl:1
	v_mov_b32_dpp v235, v243 quad_perm:[1,0,3,2] row_mask:0xf bank_mask:0xf bound_ctrl:1
	v_mov_b32_dpp v2, v245 quad_perm:[1,0,3,2] row_mask:0xf bank_mask:0xf bound_ctrl:1
	v_mov_b32_dpp v3, v246 quad_perm:[1,0,3,2] row_mask:0xf bank_mask:0xf bound_ctrl:1
	v_mov_b32_dpp v5, v247 quad_perm:[1,0,3,2] row_mask:0xf bank_mask:0xf bound_ctrl:1
	v_mov_b32_dpp v151, v248 quad_perm:[1,0,3,2] row_mask:0xf bank_mask:0xf bound_ctrl:1
	v_cvt_pk_bf16_f32 v232, v240, v232
	v_cvt_pk_bf16_f32 v233, v233, v241
	v_cndmask_b32_e64 v232, v233, v232, s[60:61]
	ds_write_b32 v208, v232 offset:512
	v_cvt_pk_bf16_f32 v234, v242, v234
	v_cvt_pk_bf16_f32 v235, v235, v243
	v_cndmask_b32_e64 v234, v235, v234, s[60:61]
	ds_write_b32 v208, v234 offset:640
	v_cvt_pk_bf16_f32 v2, v245, v2
	v_cvt_pk_bf16_f32 v3, v3, v246
	v_cndmask_b32_e64 v2, v3, v2, s[60:61]
	ds_write_b32 v208, v2 offset:768
	v_cvt_pk_bf16_f32 v5, v247, v5
	v_cvt_pk_bf16_f32 v151, v151, v248
	v_cndmask_b32_e64 v5, v151, v5, s[60:61]
	ds_write_b32 v208, v5 offset:896
	s_waitcnt vmcnt(13)
	v_lshlrev_b32_e32 v250, 16, v216
	v_mul_f32_e32 v249, v144, v7
	v_fma_f32 v240, -v17, v249, v250
	v_and_b32_e32 v250, 0xffff0000, v216
	v_mul_f32_e32 v249, v128, v7
	v_fma_f32 v241, -v17, v249, v250
	v_lshlrev_b32_e32 v250, 16, v217
	v_mul_f32_e32 v249, v112, v7
	v_fma_f32 v242, -v17, v249, v250
	v_and_b32_e32 v250, 0xffff0000, v217
	v_mul_f32_e32 v249, v96, v7
	v_fma_f32 v243, -v17, v249, v250
	v_lshlrev_b32_e32 v250, 16, v218
	v_mul_f32_e32 v249, v80, v7
	v_fma_f32 v245, -v17, v249, v250
	v_and_b32_e32 v250, 0xffff0000, v218
	v_mul_f32_e32 v249, v64, v7
	v_fma_f32 v246, -v17, v249, v250
	v_lshlrev_b32_e32 v250, 16, v219
	v_mul_f32_e32 v249, v48, v7
	v_fma_f32 v247, -v17, v249, v250
	v_and_b32_e32 v250, 0xffff0000, v219
	v_mul_f32_e32 v249, v32, v7
	v_fma_f32 v248, -v17, v249, v250
	v_mul_f32_e32 v251, v241, v241
	v_fmac_f32_e32 v251, v240, v240
	v_fmac_f32_e32 v251, v242, v242
	v_fmac_f32_e32 v251, v243, v243
	v_fmac_f32_e32 v251, v245, v245
	v_fmac_f32_e32 v251, v246, v246
	v_fmac_f32_e32 v251, v247, v247
	v_fmac_f32_e32 v251, v248, v248
	s_nop 1
	v_add_f32_dpp v251, v251, v251 quad_perm:[1,0,3,2] row_mask:0xf bank_mask:0xf bound_ctrl:1
	s_nop 1
	v_add_f32_dpp v251, v251, v251 quad_perm:[2,3,0,1] row_mask:0xf bank_mask:0xf bound_ctrl:1
	s_nop 1
	v_add_f32_dpp v251, v251, v251 row_half_mirror row_mask:0xf bank_mask:0xf bound_ctrl:1
	s_nop 1
	v_add_f32_dpp v251, v251, v251 row_mirror row_mask:0xf bank_mask:0xf bound_ctrl:1
	ds_bpermute_b32 v252, v0, v251
	s_waitcnt lgkmcnt(0)
	v_add_f32_e32 v251, v251, v252
	v_fmamk_f32 v251, v251, 0x3b800000, v238
	v_mul_f32_e32 v252, 0x4f800000, v251
	v_cmp_gt_f32_e32 vcc, s24, v251
	s_nop 1
	v_cndmask_b32_e32 v251, v251, v252, vcc
	v_sqrt_f32_e32 v252, v251
	s_nop 0
	v_add_u32_e32 v249, -1, v252
	v_fma_f32 v250, -v249, v252, v251
	v_cmp_ge_f32_e64 s[6:7], 0, v250
	v_add_u32_e32 v250, 1, v252
	s_nop 0
	v_cndmask_b32_e64 v249, v252, v249, s[6:7]
	v_fma_f32 v252, -v250, v252, v251
	v_cmp_lt_f32_e64 s[6:7], 0, v252
	s_nop 1
	v_cndmask_b32_e64 v252, v249, v250, s[6:7]
	v_mul_f32_e32 v249, 0x37800000, v252
	v_cndmask_b32_e32 v252, v252, v249, vcc
	v_cmp_class_f32_e32 vcc, v251, v239
	s_nop 1
	v_cndmask_b32_e32 v251, v252, v251, vcc
	v_div_scale_f32 v252, s[2:3], v251, v251, 1.0
	v_rcp_f32_e32 v249, v252
	s_nop 0
	v_fma_f32 v250, -v252, v249, 1.0
	v_fmac_f32_e32 v249, v250, v249
	v_div_scale_f32 v250, vcc, 1.0, v251, 1.0
	v_mul_f32_e32 v253, v250, v249
	v_fma_f32 v213, -v252, v253, v250
	v_fmac_f32_e32 v253, v213, v249
	v_fma_f32 v252, -v252, v253, v250
	v_div_fmas_f32 v252, v252, v249, v253
	v_div_fixup_f32 v253, v252, v251, 1.0
	v_mul_f32_e32 v240, v240, v253
	v_mul_f32_e32 v241, v241, v253
	v_mul_f32_e32 v242, v242, v253
	v_mul_f32_e32 v243, v243, v253
	v_mul_f32_e32 v245, v245, v253
	v_mul_f32_e32 v246, v246, v253
	v_mul_f32_e32 v247, v247, v253
	v_mul_f32_e32 v248, v248, v253
	v_mul_f32_e32 v240, v224, v240
	v_mul_f32_e32 v241, v225, v241
	v_mul_f32_e32 v242, v226, v242
	v_mul_f32_e32 v243, v227, v243
	v_mul_f32_e32 v245, v228, v245
	v_mul_f32_e32 v246, v229, v246
	v_mul_f32_e32 v247, v230, v247
	v_mul_f32_e32 v248, v231, v248
	v_mov_b32_dpp v232, v240 quad_perm:[1,0,3,2] row_mask:0xf bank_mask:0xf bound_ctrl:1
	v_mov_b32_dpp v233, v241 quad_perm:[1,0,3,2] row_mask:0xf bank_mask:0xf bound_ctrl:1
	v_mov_b32_dpp v234, v242 quad_perm:[1,0,3,2] row_mask:0xf bank_mask:0xf bound_ctrl:1
	v_mov_b32_dpp v235, v243 quad_perm:[1,0,3,2] row_mask:0xf bank_mask:0xf bound_ctrl:1
	v_mov_b32_dpp v2, v245 quad_perm:[1,0,3,2] row_mask:0xf bank_mask:0xf bound_ctrl:1
	v_mov_b32_dpp v3, v246 quad_perm:[1,0,3,2] row_mask:0xf bank_mask:0xf bound_ctrl:1
	v_mov_b32_dpp v5, v247 quad_perm:[1,0,3,2] row_mask:0xf bank_mask:0xf bound_ctrl:1
	v_mov_b32_dpp v151, v248 quad_perm:[1,0,3,2] row_mask:0xf bank_mask:0xf bound_ctrl:1
	v_cvt_pk_bf16_f32 v232, v240, v232
	v_cvt_pk_bf16_f32 v233, v233, v241
	v_cndmask_b32_e64 v232, v233, v232, s[60:61]
	ds_write_b32 v208, v232 offset:1024
	v_cvt_pk_bf16_f32 v234, v242, v234
	v_cvt_pk_bf16_f32 v235, v235, v243
	v_cndmask_b32_e64 v234, v235, v234, s[60:61]
	ds_write_b32 v208, v234 offset:1152
	v_cvt_pk_bf16_f32 v2, v245, v2
	v_cvt_pk_bf16_f32 v3, v3, v246
	v_cndmask_b32_e64 v2, v3, v2, s[60:61]
	ds_write_b32 v208, v2 offset:1280
	v_cvt_pk_bf16_f32 v5, v247, v5
	v_cvt_pk_bf16_f32 v151, v151, v248
	v_cndmask_b32_e64 v5, v151, v5, s[60:61]
	ds_write_b32 v208, v5 offset:1408
	s_waitcnt vmcnt(12)
	v_lshlrev_b32_e32 v250, 16, v220
	v_mul_f32_e32 v249, v145, v6
	v_fma_f32 v240, -v17, v249, v250
	v_and_b32_e32 v250, 0xffff0000, v220
	v_mul_f32_e32 v249, v129, v6
	v_fma_f32 v241, -v17, v249, v250
	v_lshlrev_b32_e32 v250, 16, v221
	v_mul_f32_e32 v249, v113, v6
	v_fma_f32 v242, -v17, v249, v250
	v_and_b32_e32 v250, 0xffff0000, v221
	v_mul_f32_e32 v249, v97, v6
	v_fma_f32 v243, -v17, v249, v250
	v_lshlrev_b32_e32 v250, 16, v222
	v_mul_f32_e32 v249, v81, v6
	v_fma_f32 v245, -v17, v249, v250
	v_and_b32_e32 v250, 0xffff0000, v222
	v_mul_f32_e32 v249, v65, v6
	v_fma_f32 v246, -v17, v249, v250
	v_lshlrev_b32_e32 v250, 16, v223
	v_mul_f32_e32 v249, v49, v6
	v_fma_f32 v247, -v17, v249, v250
	v_and_b32_e32 v250, 0xffff0000, v223
	v_mul_f32_e32 v249, v33, v6
	v_fma_f32 v248, -v17, v249, v250
	v_mul_f32_e32 v251, v241, v241
	v_fmac_f32_e32 v251, v240, v240
	v_fmac_f32_e32 v251, v242, v242
	v_fmac_f32_e32 v251, v243, v243
	v_fmac_f32_e32 v251, v245, v245
	v_fmac_f32_e32 v251, v246, v246
	v_fmac_f32_e32 v251, v247, v247
	v_fmac_f32_e32 v251, v248, v248
	s_nop 1
	v_add_f32_dpp v251, v251, v251 quad_perm:[1,0,3,2] row_mask:0xf bank_mask:0xf bound_ctrl:1
	s_nop 1
	v_add_f32_dpp v251, v251, v251 quad_perm:[2,3,0,1] row_mask:0xf bank_mask:0xf bound_ctrl:1
	s_nop 1
	v_add_f32_dpp v251, v251, v251 row_half_mirror row_mask:0xf bank_mask:0xf bound_ctrl:1
	s_nop 1
	v_add_f32_dpp v251, v251, v251 row_mirror row_mask:0xf bank_mask:0xf bound_ctrl:1
	ds_bpermute_b32 v252, v0, v251
	s_waitcnt lgkmcnt(0)
	v_add_f32_e32 v251, v251, v252
	v_fmamk_f32 v251, v251, 0x3b800000, v238
	v_mul_f32_e32 v252, 0x4f800000, v251
	v_cmp_gt_f32_e32 vcc, s24, v251
	s_nop 1
	v_cndmask_b32_e32 v251, v251, v252, vcc
	v_sqrt_f32_e32 v252, v251
	s_nop 0
	v_add_u32_e32 v249, -1, v252
	v_fma_f32 v250, -v249, v252, v251
	v_cmp_ge_f32_e64 s[6:7], 0, v250
	v_add_u32_e32 v250, 1, v252
	s_nop 0
	v_cndmask_b32_e64 v249, v252, v249, s[6:7]
	v_fma_f32 v252, -v250, v252, v251
	v_cmp_lt_f32_e64 s[6:7], 0, v252
	s_nop 1
	v_cndmask_b32_e64 v252, v249, v250, s[6:7]
	v_mul_f32_e32 v249, 0x37800000, v252
	v_cndmask_b32_e32 v252, v252, v249, vcc
	v_cmp_class_f32_e32 vcc, v251, v239
	s_nop 1
	v_cndmask_b32_e32 v251, v252, v251, vcc
	v_div_scale_f32 v252, s[2:3], v251, v251, 1.0
	v_rcp_f32_e32 v249, v252
	s_nop 0
	v_fma_f32 v250, -v252, v249, 1.0
	v_fmac_f32_e32 v249, v250, v249
	v_div_scale_f32 v250, vcc, 1.0, v251, 1.0
	v_mul_f32_e32 v253, v250, v249
	v_fma_f32 v213, -v252, v253, v250
	v_fmac_f32_e32 v253, v213, v249
	v_fma_f32 v252, -v252, v253, v250
	v_div_fmas_f32 v252, v252, v249, v253
	v_div_fixup_f32 v253, v252, v251, 1.0
	v_mul_f32_e32 v240, v240, v253
	v_mul_f32_e32 v241, v241, v253
	v_mul_f32_e32 v242, v242, v253
	v_mul_f32_e32 v243, v243, v253
	v_mul_f32_e32 v245, v245, v253
	v_mul_f32_e32 v246, v246, v253
	v_mul_f32_e32 v247, v247, v253
	v_mul_f32_e32 v248, v248, v253
	v_mul_f32_e32 v240, v224, v240
	v_mul_f32_e32 v241, v225, v241
	v_mul_f32_e32 v242, v226, v242
	v_mul_f32_e32 v243, v227, v243
	v_mul_f32_e32 v245, v228, v245
	v_mul_f32_e32 v246, v229, v246
	v_mul_f32_e32 v247, v230, v247
	v_mul_f32_e32 v248, v231, v248
	v_mov_b32_dpp v232, v240 quad_perm:[1,0,3,2] row_mask:0xf bank_mask:0xf bound_ctrl:1
	v_mov_b32_dpp v233, v241 quad_perm:[1,0,3,2] row_mask:0xf bank_mask:0xf bound_ctrl:1
	v_mov_b32_dpp v234, v242 quad_perm:[1,0,3,2] row_mask:0xf bank_mask:0xf bound_ctrl:1
	v_mov_b32_dpp v235, v243 quad_perm:[1,0,3,2] row_mask:0xf bank_mask:0xf bound_ctrl:1
	v_mov_b32_dpp v2, v245 quad_perm:[1,0,3,2] row_mask:0xf bank_mask:0xf bound_ctrl:1
	v_mov_b32_dpp v3, v246 quad_perm:[1,0,3,2] row_mask:0xf bank_mask:0xf bound_ctrl:1
	v_mov_b32_dpp v5, v247 quad_perm:[1,0,3,2] row_mask:0xf bank_mask:0xf bound_ctrl:1
	v_mov_b32_dpp v151, v248 quad_perm:[1,0,3,2] row_mask:0xf bank_mask:0xf bound_ctrl:1
	v_cvt_pk_bf16_f32 v232, v240, v232
	v_cvt_pk_bf16_f32 v233, v233, v241
	v_cndmask_b32_e64 v232, v233, v232, s[60:61]
	ds_write_b32 v208, v232 offset:1536
	v_cvt_pk_bf16_f32 v234, v242, v234
	v_cvt_pk_bf16_f32 v235, v235, v243
	v_cndmask_b32_e64 v234, v235, v234, s[60:61]
	ds_write_b32 v208, v234 offset:1664
	v_cvt_pk_bf16_f32 v2, v245, v2
	v_cvt_pk_bf16_f32 v3, v3, v246
	v_cndmask_b32_e64 v2, v3, v2, s[60:61]
	ds_write_b32 v208, v2 offset:1792
	v_cvt_pk_bf16_f32 v5, v247, v5
	v_cvt_pk_bf16_f32 v151, v151, v248
	v_cndmask_b32_e64 v5, v151, v5, s[60:61]
	ds_write_b32 v208, v5 offset:1920
	ds_read_b128 v[200:203], v209 offset:0
	ds_read_b128 v[204:207], v209 offset:1024
	ds_read_b128 v[216:219], v209 offset:2048
	ds_read_b128 v[220:223], v209 offset:3072
	s_waitcnt lgkmcnt(3)
	v_add_u32_e32 v249, 0x18000, v212
	global_store_dwordx4 v249, v[200:203], s[58:59] sc1
	s_waitcnt lgkmcnt(2)
	v_add_u32_e32 v249, 0x1a000, v212
	global_store_dwordx4 v249, v[204:207], s[58:59] sc1
	s_waitcnt lgkmcnt(1)
	v_add_u32_e32 v249, 0x1c000, v212
	global_store_dwordx4 v249, v[216:219], s[58:59] sc1
	s_waitcnt lgkmcnt(0)
	v_add_u32_e32 v249, 0x1e000, v212
	global_store_dwordx4 v249, v[220:223], s[58:59] sc1
	s_branch .Lep_done
